# W_in epilogue tile 5: the 8 dt_bias values of a lane loaded once per tile instead of 64 dependent load-wait steps; p0 bias reduction prefetched 16 deep
# speedup vs baseline: 1.0784x; 1.0218x over previous
; #define LAS __attribute__((address_space(3)))
; DI void p0_misc(int wv, const Params& P, LAS unsigned char* lds) {
;     ...
;     if (blockIdx.x < 2) {
;         const float* pe = P.in[blockIdx.x == 0 ? 9 : 12]; const float* w1 = P.in[blockIdx.x == 0 ? 10 : 13];
;         LAS float* red = (LAS float*)lds; const int j = tid_ & 63, part = tid_ >> 6; float s = 0.f;
;         for (int k = part; k < 2048; k += 8) s += pe[k] * w1[k * 64 + j];
;         red[part * 64 + j] = s; __syncthreads();
;         if (tid_ < 64) { float t = 0.f; for (int p = 0; p < 8; ++p) t += red[p * 64 + j]; ((float*)(ws_ + WS_PEB))[blockIdx.x * 64 + j] = t; }
.LBB0_310:
	s_or_b64 exec, exec, s[16:17]
	s_cmp_lt_u32 s33, 2
	s_cbranch_scc0 .LBB0_318
	v_ashrrev_i32_e32 v2, 6, v6
	s_movk_i32 s2, 0x800
	v_and_b32_e32 v4, 63, v7
	v_cmp_gt_i32_e32 vcc, s2, v2
	v_mov_b32_e32 v5, 0
	s_and_saveexec_b64 s[2:3], vcc
	s_cbranch_execz .LBB0_315
	s_cmp_eq_u32 s33, 0
	s_movk_i32 s4, 0x48
	s_cselect_b32 s4, s4, 0x60
	s_movk_i32 s5, 0x50
	s_cselect_b32 s5, s5, 0x68
	s_add_u32 s6, s0, s4
	s_addc_u32 s7, s1, 0
	s_add_u32 s8, s0, s5
	s_addc_u32 s9, s1, 0
	s_load_dwordx2 s[12:13], s[6:7], 0x0
	s_load_dwordx2 s[4:5], s[8:9], 0x0
	v_ashrrev_i32_e32 v3, 31, v2
	v_add_u32_e32 v7, -8, v2
	v_lshl_or_b32 v0, v2, 6, v4
	s_waitcnt lgkmcnt(0)
	v_lshl_add_u64 v[2:3], v[2:3], 2, s[12:13]
	v_mov_b32_e32 v5, 0
	s_mov_b64 s[6:7], 0
	v_lshlrev_b32_e32 v8, 2, v0
	v_lshl_add_u32 v9, v7, 2, 32
	s_mov_b32 s8, 16
.Lbias_loop:
	global_load_dword v64, v9, s[12:13]
	global_load_dword v65, v9, s[12:13] offset:32
	global_load_dword v66, v9, s[12:13] offset:64
	global_load_dword v67, v9, s[12:13] offset:96
	global_load_dword v68, v9, s[12:13] offset:128
	global_load_dword v69, v9, s[12:13] offset:160
	global_load_dword v70, v9, s[12:13] offset:192
	global_load_dword v71, v9, s[12:13] offset:224
	global_load_dword v72, v9, s[12:13] offset:256
	global_load_dword v73, v9, s[12:13] offset:288
	global_load_dword v74, v9, s[12:13] offset:320
	global_load_dword v75, v9, s[12:13] offset:352
	global_load_dword v76, v9, s[12:13] offset:384
	global_load_dword v77, v9, s[12:13] offset:416
	global_load_dword v78, v9, s[12:13] offset:448
	global_load_dword v79, v9, s[12:13] offset:480
	global_load_dword v80, v8, s[4:5]
	v_add_u32_e32 v8, 0x800, v8
	global_load_dword v81, v8, s[4:5]
	v_add_u32_e32 v8, 0x800, v8
	global_load_dword v82, v8, s[4:5]
	v_add_u32_e32 v8, 0x800, v8
	global_load_dword v83, v8, s[4:5]
	v_add_u32_e32 v8, 0x800, v8
	global_load_dword v84, v8, s[4:5]
	v_add_u32_e32 v8, 0x800, v8
	global_load_dword v85, v8, s[4:5]
	v_add_u32_e32 v8, 0x800, v8
	global_load_dword v86, v8, s[4:5]
	v_add_u32_e32 v8, 0x800, v8
	global_load_dword v87, v8, s[4:5]
	v_add_u32_e32 v8, 0x800, v8
	global_load_dword v88, v8, s[4:5]
	v_add_u32_e32 v8, 0x800, v8
	global_load_dword v89, v8, s[4:5]
	v_add_u32_e32 v8, 0x800, v8
	global_load_dword v90, v8, s[4:5]
	v_add_u32_e32 v8, 0x800, v8
	global_load_dword v91, v8, s[4:5]
	v_add_u32_e32 v8, 0x800, v8
	global_load_dword v92, v8, s[4:5]
	v_add_u32_e32 v8, 0x800, v8
	global_load_dword v93, v8, s[4:5]
	v_add_u32_e32 v8, 0x800, v8
	global_load_dword v94, v8, s[4:5]
	v_add_u32_e32 v8, 0x800, v8
	global_load_dword v95, v8, s[4:5]
	v_add_u32_e32 v8, 0x800, v8
	v_add_u32_e32 v9, 0x200, v9
	s_sub_i32 s8, s8, 1
	s_cmp_lg_u32 s8, 0
	s_waitcnt vmcnt(0)
	v_fmac_f32_e32 v5, v64, v80
	v_fmac_f32_e32 v5, v65, v81
	v_fmac_f32_e32 v5, v66, v82
	v_fmac_f32_e32 v5, v67, v83
	v_fmac_f32_e32 v5, v68, v84
	v_fmac_f32_e32 v5, v69, v85
	v_fmac_f32_e32 v5, v70, v86
	v_fmac_f32_e32 v5, v71, v87
	v_fmac_f32_e32 v5, v72, v88
	v_fmac_f32_e32 v5, v73, v89
	v_fmac_f32_e32 v5, v74, v90
	v_fmac_f32_e32 v5, v75, v91
	v_fmac_f32_e32 v5, v76, v92
	v_fmac_f32_e32 v5, v77, v93
	v_fmac_f32_e32 v5, v78, v94
	v_fmac_f32_e32 v5, v79, v95
	s_cbranch_scc1 .Lbias_loop
	s_or_b64 exec, exec, s[6:7]

; #define TS_(e) { const unsigned w0_ = pk2(ta0[e], ta1[e]); vt[(size_t)(e) * SEQ] = (bf16_t)(w0_ & 0xffff); vt[(size_t)((e) + 4) * SEQ] = (bf16_t)(w0_ >> 16); }
; #define GV_(n, e) { const int c_ = cb + 4 * (n) + (e); const float v_ = (n) ? tb1[e] : tb0[e]; if (c_ < 24) GATES[(size_t)row * 24 + c_] = sigmoidf_(v_); else if (c_ < 40) DT[(size_t)row * 16 + c_ - 24] = softplus_fast(v_ + dt_bias[c_ - 24]); }
;     DI void operator()(const Acc& acc, const Unit& u, int wr, int wc, int fr, int fq) const {
;     ...
;                 else { bf16_t* vt = VWT + ((size_t)(b * 2 + h) * 64 + d0) * SEQ + t; const f32x4 ta0 = acc[ai][0][m][0], ta1 = acc[ai][0][m][1]; TS_(0) TS_(1) TS_(2) TS_(3)
;                   const int cb = wc * 32 + 8 * fq; const f32x4 tb0 = acc[ai][1][m][0], tb1 = acc[ai][1][m][1];
;                   if (cb < 40) { GV_(0, 0) GV_(0, 1) GV_(0, 2) GV_(0, 3) GV_(1, 0) GV_(1, 1) GV_(1, 2) GV_(1, 3) } } )
.LBB0_879:
	s_andn2_b64 vcc, exec, s[4:5]
	s_cbranch_vccnz .LBB0_1176
	s_cmp_lg_u32 s86, 4
	v_lshlrev_b32_e32 v130, 3, v196
	v_readlane_b32 s4, v252, 28
	s_cselect_b64 s[24:25], -1, 0
	v_add_u32_e32 v152, s36, v130
	v_add_u32_e32 v128, s4, v130
	s_lshl_b32 s4, s88, 8
	s_add_i32 s4, s4, s97
	v_add_u32_e32 v182, s4, v195
	v_ashrrev_i32_e32 v129, 31, v128
	v_readlane_b32 s4, v252, 22
	v_lshlrev_b64 v[184:185], 14, v[128:129]
	v_readlane_b32 s5, v252, 23
	v_ashrrev_i32_e32 v131, 31, v152
	v_mov_b32_e32 v130, v152
	v_or_b32_e32 v174, 1, v152
	v_or_b32_e32 v170, 2, v152
	v_or_b32_e32 v166, 3, v152
	v_or_b32_e32 v162, 4, v152
	v_or_b32_e32 v140, 5, v152
	v_or_b32_e32 v136, 6, v152
	v_or_b32_e32 v132, 7, v152
	v_lshl_add_u64 v[180:181], s[4:5], 0, v[184:185]
	v_cmp_gt_i32_e64 s[20:21], 40, v152
	v_cmp_lt_i32_e64 s[18:19], 23, v152
	v_lshl_add_u64 v[176:177], v[152:153], 2, s[42:43]
	v_lshl_add_u64 v[178:179], v[130:131], 2, s[40:41]
	v_cmp_lt_i32_e64 s[16:17], 23, v174
	v_mov_b32_e32 v175, v153
	v_ashrrev_i32_e32 v173, 31, v174
	v_mov_b32_e32 v172, v174
	v_cmp_lt_i32_e64 s[14:15], 23, v170
	v_mov_b32_e32 v171, v153
	v_ashrrev_i32_e32 v169, 31, v170
	v_mov_b32_e32 v168, v170
	v_cmp_lt_i32_e64 s[12:13], 23, v166
	v_mov_b32_e32 v167, v153
	v_ashrrev_i32_e32 v165, 31, v166
	v_mov_b32_e32 v164, v166
	v_cmp_lt_i32_e64 s[10:11], 23, v162
	v_mov_b32_e32 v163, v153
	v_ashrrev_i32_e32 v143, 31, v162
	v_mov_b32_e32 v142, v162
	v_cmp_lt_i32_e64 s[8:9], 23, v140
	v_mov_b32_e32 v141, v153
	v_ashrrev_i32_e32 v139, 31, v140
	v_mov_b32_e32 v138, v140
	v_cmp_lt_i32_e64 s[6:7], 23, v136
	v_mov_b32_e32 v137, v153
	v_ashrrev_i32_e32 v135, 31, v136
	v_mov_b32_e32 v134, v136
	v_cmp_lt_i32_e64 s[4:5], 23, v132
	v_mov_b32_e32 v133, v153
	v_ashrrev_i32_e32 v131, 31, v132
	v_mov_b32_e32 v130, v132
	v_and_b32_e32 v186, 0x1fff, v182
	v_ashrrev_i32_e32 v187, 13, v182
	s_mov_b64 s[22:23], -1
	s_and_b64 vcc, exec, s[24:25]
	s_cbranch_vccz .LBB0_915
	v_lshl_or_b32 v198, v187, 1, s63
	v_ashrrev_i32_e32 v199, 31, v198
	v_lshlrev_b64 v[198:199], 20, v[198:199]
	v_lshl_add_u64 v[198:199], v[180:181], 0, v[198:199]
	v_lshlrev_b32_e32 v200, 1, v186
	v_mov_b32_e32 v201, v153
	v_lshl_add_u64 v[198:199], v[198:199], 0, v[200:201]
	v_add_co_u32_e32 v200, vcc, 0x10000, v198
	v_cvt_pk_bf16_f32 v183, v124, v120
	s_nop 0
	v_addc_co_u32_e32 v201, vcc, 0, v199, vcc
	flat_store_short_d16_hi v[200:201], v183
	v_add_co_u32_e32 v200, vcc, 0x4000, v198
	flat_store_short v[198:199], v183
	v_cvt_pk_bf16_f32 v183, v125, v121
	v_addc_co_u32_e32 v201, vcc, 0, v199, vcc
	flat_store_short v[200:201], v183
	v_add_co_u32_e32 v200, vcc, 0x14000, v198
	s_nop 1
	v_addc_co_u32_e32 v201, vcc, 0, v199, vcc
	flat_store_short_d16_hi v[200:201], v183
	v_add_co_u32_e32 v200, vcc, 0x8000, v198
	v_cvt_pk_bf16_f32 v183, v126, v122
	s_nop 0
	v_addc_co_u32_e32 v201, vcc, 0, v199, vcc
	flat_store_short v[200:201], v183
	v_add_co_u32_e32 v200, vcc, 0x18000, v198
	s_nop 1
	v_addc_co_u32_e32 v201, vcc, 0, v199, vcc
	flat_store_short_d16_hi v[200:201], v183
	v_add_co_u32_e32 v200, vcc, 0xc000, v198
	v_cvt_pk_bf16_f32 v183, v127, v123
	s_nop 0
	v_addc_co_u32_e32 v201, vcc, 0, v199, vcc
	v_add_co_u32_e32 v198, vcc, 0x1c000, v198
	flat_store_short v[200:201], v183
	s_nop 0
	v_addc_co_u32_e32 v199, vcc, 0, v199, vcc
	flat_store_short_d16_hi v[198:199], v183
	s_and_saveexec_b64 s[90:91], s[20:21]
	s_cbranch_execz .LBB0_914
	v_ashrrev_i32_e32 v183, 31, v182
	s_and_saveexec_b64 s[22:23], s[18:19]
	s_xor_b64 s[92:93], exec, s[22:23]
	s_cbranch_execz .LBB0_898
	v_lshl_add_u64 v[198:199], v[152:153], 2, s[28:29]
	global_load_dword v228, v[198:199], off offset:-96
	global_load_dword v229, v[198:199], off offset:-92
	global_load_dword v230, v[198:199], off offset:-88
	global_load_dword v231, v[198:199], off offset:-84
	global_load_dword v232, v[198:199], off offset:-80
	global_load_dword v233, v[198:199], off offset:-76
	global_load_dword v234, v[198:199], off offset:-72
	global_load_dword v235, v[198:199], off offset:-68
	s_waitcnt vmcnt(0)
	v_mov_b32_e32 v197, v228
	v_add_f32_e32 v197, v116, v197
	v_max_f32_e32 v198, 0, v197
	v_mul_f32_e64 v197, |v197|, s46
	v_exp_f32_e32 v197, v197
	s_nop 0
	v_add_f32_e32 v197, 1.0, v197
	v_cmp_gt_f32_e32 vcc, s47, v197
	s_nop 1
	v_cndmask_b32_e64 v199, 0, 32, vcc
	v_ldexp_f32 v197, v197, v199
	v_log_f32_e32 v197, v197
	s_nop 0
	v_mul_f32_e32 v199, 0x3f317217, v197
	v_fma_f32 v199, v197, s94, -v199
	v_fmac_f32_e32 v199, 0x3377d1cf, v197
	v_fmac_f32_e32 v199, 0x3f317217, v197
	v_cmp_lt_f32_e64 s[22:23], |v197|, s51
	s_nop 1
	v_cndmask_b32_e64 v197, v197, v199, s[22:23]
	v_cndmask_b32_e32 v199, 0, v194, vcc
	v_sub_f32_e32 v197, v197, v199
	v_add_f32_e32 v197, v198, v197
	v_lshlrev_b64 v[198:199], 6, v[182:183]
	v_lshl_add_u64 v[198:199], v[176:177], 0, v[198:199]
	v_add_co_u32_e32 v198, vcc, 0xffffffa0, v198
	s_nop 1
	v_addc_co_u32_e32 v199, vcc, -1, v199, vcc
	flat_store_dword v[198:199], v197
	s_andn2_saveexec_b64 s[22:23], s[92:93]
	s_cbranch_execnz .LBB0_899

; DI float softplus_fast(float x) { return fmaxf(x, 0.f) + __logf(1.f + __expf(-fabsf(x))); }
.LBB0_885:
	v_lshl_add_u64 v[198:199], v[152:153], 2, s[28:29]
	v_mov_b32_e32 v197, v229
	v_add_f32_e32 v197, v117, v197
	v_max_f32_e32 v198, 0, v197
	v_mul_f32_e64 v197, |v197|, s46
	v_exp_f32_e32 v197, v197
	s_nop 0
	v_add_f32_e32 v197, 1.0, v197
	v_cmp_gt_f32_e32 vcc, s47, v197
	s_nop 1
	v_cndmask_b32_e64 v199, 0, 32, vcc
	v_ldexp_f32 v197, v197, v199
	v_log_f32_e32 v197, v197
	s_nop 0
	v_mul_f32_e32 v199, 0x3f317217, v197
	v_fma_f32 v199, v197, s94, -v199
	v_fmac_f32_e32 v199, 0x3377d1cf, v197
	v_fmac_f32_e32 v199, 0x3f317217, v197
	v_cmp_lt_f32_e64 s[22:23], |v197|, s51
	s_nop 1
	v_cndmask_b32_e64 v197, v197, v199, s[22:23]
	v_cndmask_b32_e32 v199, 0, v194, vcc
	v_sub_f32_e32 v197, v197, v199
	v_add_f32_e32 v197, v198, v197
	v_lshlrev_b64 v[198:199], 6, v[182:183]
	v_lshl_add_u64 v[198:199], s[42:43], 0, v[198:199]
	v_lshl_add_u64 v[198:199], v[174:175], 2, v[198:199]
	v_add_co_u32_e32 v198, vcc, 0xffffffa0, v198
	s_nop 1
	v_addc_co_u32_e32 v199, vcc, -1, v199, vcc
	flat_store_dword v[198:199], v197
	s_andn2_saveexec_b64 s[22:23], s[92:93]
	s_cbranch_execnz .LBB0_901

; DI float softplus_fast(float x) { return fmaxf(x, 0.f) + __logf(1.f + __expf(-fabsf(x))); }
.LBB0_887:
	v_lshl_add_u64 v[198:199], v[152:153], 2, s[28:29]
	v_mov_b32_e32 v197, v230
	v_add_f32_e32 v197, v118, v197
	v_max_f32_e32 v198, 0, v197
	v_mul_f32_e64 v197, |v197|, s46
	v_exp_f32_e32 v197, v197
	s_nop 0
	v_add_f32_e32 v197, 1.0, v197
	v_cmp_gt_f32_e32 vcc, s47, v197
	s_nop 1
	v_cndmask_b32_e64 v199, 0, 32, vcc
	v_ldexp_f32 v197, v197, v199
	v_log_f32_e32 v197, v197
	s_nop 0
	v_mul_f32_e32 v199, 0x3f317217, v197
	v_fma_f32 v199, v197, s94, -v199
	v_fmac_f32_e32 v199, 0x3377d1cf, v197
	v_fmac_f32_e32 v199, 0x3f317217, v197
	v_cmp_lt_f32_e64 s[22:23], |v197|, s51
	s_nop 1
	v_cndmask_b32_e64 v197, v197, v199, s[22:23]
	v_cndmask_b32_e32 v199, 0, v194, vcc
	v_sub_f32_e32 v197, v197, v199
	v_add_f32_e32 v197, v198, v197
	v_lshlrev_b64 v[198:199], 6, v[182:183]
	v_lshl_add_u64 v[198:199], s[42:43], 0, v[198:199]
	v_lshl_add_u64 v[198:199], v[170:171], 2, v[198:199]
	v_add_co_u32_e32 v198, vcc, 0xffffffa0, v198
	s_nop 1
	v_addc_co_u32_e32 v199, vcc, -1, v199, vcc
	flat_store_dword v[198:199], v197
	s_andn2_saveexec_b64 s[22:23], s[92:93]
	s_cbranch_execnz .LBB0_903

; DI float softplus_fast(float x) { return fmaxf(x, 0.f) + __logf(1.f + __expf(-fabsf(x))); }
.LBB0_889:
	v_lshl_add_u64 v[198:199], v[152:153], 2, s[28:29]
	v_mov_b32_e32 v197, v231
	v_add_f32_e32 v197, v119, v197
	v_max_f32_e32 v198, 0, v197
	v_mul_f32_e64 v197, |v197|, s46
	v_exp_f32_e32 v197, v197
	s_nop 0
	v_add_f32_e32 v197, 1.0, v197
	v_cmp_gt_f32_e32 vcc, s47, v197
	s_nop 1
	v_cndmask_b32_e64 v199, 0, 32, vcc
	v_ldexp_f32 v197, v197, v199
	v_log_f32_e32 v197, v197
	s_nop 0
	v_mul_f32_e32 v199, 0x3f317217, v197
	v_fma_f32 v199, v197, s94, -v199
	v_fmac_f32_e32 v199, 0x3377d1cf, v197
	v_fmac_f32_e32 v199, 0x3f317217, v197
	v_cmp_lt_f32_e64 s[22:23], |v197|, s51
	s_nop 1
	v_cndmask_b32_e64 v197, v197, v199, s[22:23]
	v_cndmask_b32_e32 v199, 0, v194, vcc
	v_sub_f32_e32 v197, v197, v199
	v_add_f32_e32 v197, v198, v197
	v_lshlrev_b64 v[198:199], 6, v[182:183]
	v_lshl_add_u64 v[198:199], s[42:43], 0, v[198:199]
	v_lshl_add_u64 v[198:199], v[166:167], 2, v[198:199]
	v_add_co_u32_e32 v198, vcc, 0xffffffa0, v198
	s_nop 1
	v_addc_co_u32_e32 v199, vcc, -1, v199, vcc
	flat_store_dword v[198:199], v197
	s_andn2_saveexec_b64 s[22:23], s[92:93]
	s_cbranch_execnz .LBB0_905

; DI float softplus_fast(float x) { return fmaxf(x, 0.f) + __logf(1.f + __expf(-fabsf(x))); }
.LBB0_891:
	v_lshl_add_u64 v[198:199], v[152:153], 2, s[28:29]
	v_mov_b32_e32 v197, v232
	v_add_f32_e32 v197, v112, v197
	v_max_f32_e32 v198, 0, v197
	v_mul_f32_e64 v197, |v197|, s46
	v_exp_f32_e32 v197, v197
	s_nop 0
	v_add_f32_e32 v197, 1.0, v197
	v_cmp_gt_f32_e32 vcc, s47, v197
	s_nop 1
	v_cndmask_b32_e64 v199, 0, 32, vcc
	v_ldexp_f32 v197, v197, v199
	v_log_f32_e32 v197, v197
	s_nop 0
	v_mul_f32_e32 v199, 0x3f317217, v197
	v_fma_f32 v199, v197, s94, -v199
	v_fmac_f32_e32 v199, 0x3377d1cf, v197
	v_fmac_f32_e32 v199, 0x3f317217, v197
	v_cmp_lt_f32_e64 s[22:23], |v197|, s51
	s_nop 1
	v_cndmask_b32_e64 v197, v197, v199, s[22:23]
	v_cndmask_b32_e32 v199, 0, v194, vcc
	v_sub_f32_e32 v197, v197, v199
	v_add_f32_e32 v197, v198, v197
	v_lshlrev_b64 v[198:199], 6, v[182:183]
	v_lshl_add_u64 v[198:199], s[42:43], 0, v[198:199]
	v_lshl_add_u64 v[198:199], v[162:163], 2, v[198:199]
	v_add_co_u32_e32 v198, vcc, 0xffffffa0, v198
	s_nop 1
	v_addc_co_u32_e32 v199, vcc, -1, v199, vcc
	flat_store_dword v[198:199], v197
	s_andn2_saveexec_b64 s[22:23], s[92:93]
	s_cbranch_execnz .LBB0_907

; DI float softplus_fast(float x) { return fmaxf(x, 0.f) + __logf(1.f + __expf(-fabsf(x))); }
.LBB0_893:
	v_lshl_add_u64 v[198:199], v[152:153], 2, s[28:29]
	v_mov_b32_e32 v197, v233
	v_add_f32_e32 v197, v113, v197
	v_max_f32_e32 v198, 0, v197
	v_mul_f32_e64 v197, |v197|, s46
	v_exp_f32_e32 v197, v197
	s_nop 0
	v_add_f32_e32 v197, 1.0, v197
	v_cmp_gt_f32_e32 vcc, s47, v197
	s_nop 1
	v_cndmask_b32_e64 v199, 0, 32, vcc
	v_ldexp_f32 v197, v197, v199
	v_log_f32_e32 v197, v197
	s_nop 0
	v_mul_f32_e32 v199, 0x3f317217, v197
	v_fma_f32 v199, v197, s94, -v199
	v_fmac_f32_e32 v199, 0x3377d1cf, v197
	v_fmac_f32_e32 v199, 0x3f317217, v197
	v_cmp_lt_f32_e64 s[22:23], |v197|, s51
	s_nop 1
	v_cndmask_b32_e64 v197, v197, v199, s[22:23]
	v_cndmask_b32_e32 v199, 0, v194, vcc
	v_sub_f32_e32 v197, v197, v199
	v_add_f32_e32 v197, v198, v197
	v_lshlrev_b64 v[198:199], 6, v[182:183]
	v_lshl_add_u64 v[198:199], s[42:43], 0, v[198:199]
	v_lshl_add_u64 v[198:199], v[140:141], 2, v[198:199]
	v_add_co_u32_e32 v198, vcc, 0xffffffa0, v198
	s_nop 1
	v_addc_co_u32_e32 v199, vcc, -1, v199, vcc
	flat_store_dword v[198:199], v197
	s_andn2_saveexec_b64 s[22:23], s[92:93]
	s_cbranch_execnz .LBB0_909

; DI float softplus_fast(float x) { return fmaxf(x, 0.f) + __logf(1.f + __expf(-fabsf(x))); }
.LBB0_895:
	v_lshl_add_u64 v[198:199], v[152:153], 2, s[28:29]
	v_mov_b32_e32 v197, v234
	v_add_f32_e32 v197, v114, v197
	v_max_f32_e32 v198, 0, v197
	v_mul_f32_e64 v197, |v197|, s46
	v_exp_f32_e32 v197, v197
	s_nop 0
	v_add_f32_e32 v197, 1.0, v197
	v_cmp_gt_f32_e32 vcc, s47, v197
	s_nop 1
	v_cndmask_b32_e64 v199, 0, 32, vcc
	v_ldexp_f32 v197, v197, v199
	v_log_f32_e32 v197, v197
	s_nop 0
	v_mul_f32_e32 v199, 0x3f317217, v197
	v_fma_f32 v199, v197, s94, -v199
	v_fmac_f32_e32 v199, 0x3377d1cf, v197
	v_fmac_f32_e32 v199, 0x3f317217, v197
	v_cmp_lt_f32_e64 s[22:23], |v197|, s51
	s_nop 1
	v_cndmask_b32_e64 v197, v197, v199, s[22:23]
	v_cndmask_b32_e32 v199, 0, v194, vcc
	v_sub_f32_e32 v197, v197, v199
	v_add_f32_e32 v197, v198, v197
	v_lshlrev_b64 v[198:199], 6, v[182:183]
	v_lshl_add_u64 v[198:199], s[42:43], 0, v[198:199]
	v_lshl_add_u64 v[198:199], v[136:137], 2, v[198:199]
	v_add_co_u32_e32 v198, vcc, 0xffffffa0, v198
	s_nop 1
	v_addc_co_u32_e32 v199, vcc, -1, v199, vcc
	flat_store_dword v[198:199], v197
	s_andn2_saveexec_b64 s[22:23], s[92:93]
	s_cbranch_execnz .LBB0_911

; DI float softplus_fast(float x) { return fmaxf(x, 0.f) + __logf(1.f + __expf(-fabsf(x))); }
.LBB0_897:
	v_lshl_add_u64 v[198:199], v[152:153], 2, s[28:29]
	v_mov_b32_e32 v197, v235
	v_add_f32_e32 v197, v115, v197
	v_max_f32_e32 v198, 0, v197
	v_mul_f32_e64 v197, |v197|, s46
	v_exp_f32_e32 v197, v197
	s_nop 0
	v_add_f32_e32 v197, 1.0, v197
	v_cmp_gt_f32_e32 vcc, s47, v197
	s_nop 1
	v_cndmask_b32_e64 v199, 0, 32, vcc
	v_ldexp_f32 v197, v197, v199
	v_log_f32_e32 v197, v197
	s_nop 0
	v_mul_f32_e32 v199, 0x3f317217, v197
	v_fma_f32 v199, v197, s94, -v199
	v_fmac_f32_e32 v199, 0x3377d1cf, v197
	v_fmac_f32_e32 v199, 0x3f317217, v197
	v_cmp_lt_f32_e64 s[22:23], |v197|, s51
	s_nop 1
	v_cndmask_b32_e64 v197, v197, v199, s[22:23]
	v_cndmask_b32_e32 v199, 0, v194, vcc
	v_sub_f32_e32 v197, v197, v199
	v_add_f32_e32 v197, v198, v197
	v_lshlrev_b64 v[198:199], 6, v[182:183]
	v_lshl_add_u64 v[198:199], s[42:43], 0, v[198:199]
	v_lshl_add_u64 v[198:199], v[132:133], 2, v[198:199]
	v_add_co_u32_e32 v198, vcc, 0xffffffa0, v198
	s_nop 1
	v_addc_co_u32_e32 v199, vcc, -1, v199, vcc
	flat_store_dword v[198:199], v197
	s_andn2_saveexec_b64 s[22:23], s[92:93]
	s_cbranch_execnz .LBB0_913
	s_branch .LBB0_914

; #define TS_(e) { const unsigned w0_ = pk2(ta0[e], ta1[e]); vt[(size_t)(e) * SEQ] = (bf16_t)(w0_ & 0xffff); vt[(size_t)((e) + 4) * SEQ] = (bf16_t)(w0_ >> 16); }
; #define GV_(n, e) { const int c_ = cb + 4 * (n) + (e); const float v_ = (n) ? tb1[e] : tb0[e]; if (c_ < 24) GATES[(size_t)row * 24 + c_] = sigmoidf_(v_); else if (c_ < 40) DT[(size_t)row * 16 + c_ - 24] = softplus_fast(v_ + dt_bias[c_ - 24]); }
;     DI void operator()(const Acc& acc, const Unit& u, int wr, int wc, int fr, int fq) const {
;     ...
;                 else { bf16_t* vt = VWT + ((size_t)(b * 2 + h) * 64 + d0) * SEQ + t; const f32x4 ta0 = acc[ai][0][m][0], ta1 = acc[ai][0][m][1]; TS_(0) TS_(1) TS_(2) TS_(3)
;                   const int cb = wc * 32 + 8 * fq; const f32x4 tb0 = acc[ai][1][m][0], tb1 = acc[ai][1][m][1];
;                   if (cb < 40) { GV_(0, 0) GV_(0, 1) GV_(0, 2) GV_(0, 3) GV_(1, 0) GV_(1, 1) GV_(1, 2) GV_(1, 3) } } )
.LBB0_917:
	v_add_u32_e32 v186, 16, v182
	v_cndmask_b32_e64 v187, 0, 1, s[24:25]
	v_and_b32_e32 v183, 0x1fff, v186
	v_ashrrev_i32_e32 v197, 13, v186
	v_cmp_ne_u32_e64 s[22:23], 1, v187
	s_andn2_b64 vcc, exec, s[24:25]
	s_mov_b64 s[24:25], -1
	s_cbranch_vccnz .LBB0_952
	v_lshl_or_b32 v198, v197, 1, s63
	v_ashrrev_i32_e32 v199, 31, v198
	v_lshlrev_b64 v[198:199], 20, v[198:199]
	v_lshl_add_u64 v[198:199], v[180:181], 0, v[198:199]
	v_lshlrev_b32_e32 v200, 1, v183
	v_mov_b32_e32 v201, v153
	v_lshl_add_u64 v[198:199], v[198:199], 0, v[200:201]
	v_add_co_u32_e32 v200, vcc, 0x10000, v198
	v_cvt_pk_bf16_f32 v187, v108, v104
	s_nop 0
	v_addc_co_u32_e32 v201, vcc, 0, v199, vcc
	flat_store_short_d16_hi v[200:201], v187
	v_add_co_u32_e32 v200, vcc, 0x4000, v198
	flat_store_short v[198:199], v187
	v_cvt_pk_bf16_f32 v187, v109, v105
	v_addc_co_u32_e32 v201, vcc, 0, v199, vcc
	flat_store_short v[200:201], v187
	v_add_co_u32_e32 v200, vcc, 0x14000, v198
	s_nop 1
	v_addc_co_u32_e32 v201, vcc, 0, v199, vcc
	flat_store_short_d16_hi v[200:201], v187
	v_add_co_u32_e32 v200, vcc, 0x8000, v198
	v_cvt_pk_bf16_f32 v187, v110, v106
	s_nop 0
	v_addc_co_u32_e32 v201, vcc, 0, v199, vcc
	flat_store_short v[200:201], v187
	v_add_co_u32_e32 v200, vcc, 0x18000, v198
	s_nop 1
	v_addc_co_u32_e32 v201, vcc, 0, v199, vcc
	flat_store_short_d16_hi v[200:201], v187
	v_add_co_u32_e32 v200, vcc, 0xc000, v198
	v_cvt_pk_bf16_f32 v187, v111, v107
	s_nop 0
	v_addc_co_u32_e32 v201, vcc, 0, v199, vcc
	v_add_co_u32_e32 v198, vcc, 0x1c000, v198
	flat_store_short v[200:201], v187
	s_nop 0
	v_addc_co_u32_e32 v199, vcc, 0, v199, vcc
	flat_store_short_d16_hi v[198:199], v187
	s_and_saveexec_b64 s[90:91], s[20:21]
	s_cbranch_execz .LBB0_951
	v_ashrrev_i32_e32 v187, 31, v186
	s_and_saveexec_b64 s[24:25], s[18:19]
	s_xor_b64 s[92:93], exec, s[24:25]
	s_cbranch_execz .LBB0_935
	v_lshl_add_u64 v[198:199], v[152:153], 2, s[28:29]
	v_mov_b32_e32 v198, v228
	v_add_f32_e32 v198, v100, v198
	v_max_f32_e32 v199, 0, v198
	v_mul_f32_e64 v198, |v198|, s46
	v_exp_f32_e32 v198, v198
	s_nop 0
	v_add_f32_e32 v198, 1.0, v198
	v_cmp_gt_f32_e32 vcc, s47, v198
	s_nop 1
	v_cndmask_b32_e64 v200, 0, 32, vcc
	v_ldexp_f32 v198, v198, v200
	v_log_f32_e32 v198, v198
	s_nop 0
	v_mul_f32_e32 v200, 0x3f317217, v198
	v_fma_f32 v200, v198, s94, -v200
	v_fmac_f32_e32 v200, 0x3377d1cf, v198
	v_fmac_f32_e32 v200, 0x3f317217, v198
	v_cmp_lt_f32_e64 s[24:25], |v198|, s51
	s_nop 1
	v_cndmask_b32_e64 v198, v198, v200, s[24:25]
	v_cndmask_b32_e32 v200, 0, v194, vcc
	v_sub_f32_e32 v198, v198, v200
	v_add_f32_e32 v200, v199, v198
	v_lshlrev_b64 v[198:199], 6, v[186:187]
	v_lshl_add_u64 v[198:199], v[176:177], 0, v[198:199]
	v_add_co_u32_e32 v198, vcc, 0xffffffa0, v198
	s_nop 1
	v_addc_co_u32_e32 v199, vcc, -1, v199, vcc
	flat_store_dword v[198:199], v200
	s_andn2_saveexec_b64 s[24:25], s[92:93]
	s_cbranch_execnz .LBB0_936

; DI float softplus_fast(float x) { return fmaxf(x, 0.f) + __logf(1.f + __expf(-fabsf(x))); }
.LBB0_922:
	v_lshl_add_u64 v[198:199], v[152:153], 2, s[28:29]
	v_mov_b32_e32 v198, v229
	v_add_f32_e32 v198, v101, v198
	v_max_f32_e32 v199, 0, v198
	v_mul_f32_e64 v198, |v198|, s46
	v_exp_f32_e32 v198, v198
	s_nop 0
	v_add_f32_e32 v198, 1.0, v198
	v_cmp_gt_f32_e32 vcc, s47, v198
	s_nop 1
	v_cndmask_b32_e64 v200, 0, 32, vcc
	v_ldexp_f32 v198, v198, v200
	v_log_f32_e32 v198, v198
	s_nop 0
	v_mul_f32_e32 v200, 0x3f317217, v198
	v_fma_f32 v200, v198, s94, -v200
	v_fmac_f32_e32 v200, 0x3377d1cf, v198
	v_fmac_f32_e32 v200, 0x3f317217, v198
	v_cmp_lt_f32_e64 s[24:25], |v198|, s51
	s_nop 1
	v_cndmask_b32_e64 v198, v198, v200, s[24:25]
	v_cndmask_b32_e32 v200, 0, v194, vcc
	v_sub_f32_e32 v198, v198, v200
	v_add_f32_e32 v200, v199, v198
	v_lshlrev_b64 v[198:199], 6, v[186:187]
	v_lshl_add_u64 v[198:199], s[42:43], 0, v[198:199]
	v_lshl_add_u64 v[198:199], v[174:175], 2, v[198:199]
	v_add_co_u32_e32 v198, vcc, 0xffffffa0, v198
	s_nop 1
	v_addc_co_u32_e32 v199, vcc, -1, v199, vcc
	flat_store_dword v[198:199], v200
	s_andn2_saveexec_b64 s[24:25], s[92:93]
	s_cbranch_execnz .LBB0_938

; DI float softplus_fast(float x) { return fmaxf(x, 0.f) + __logf(1.f + __expf(-fabsf(x))); }
.LBB0_924:
	v_lshl_add_u64 v[198:199], v[152:153], 2, s[28:29]
	v_mov_b32_e32 v198, v230
	v_add_f32_e32 v198, v102, v198
	v_max_f32_e32 v199, 0, v198
	v_mul_f32_e64 v198, |v198|, s46
	v_exp_f32_e32 v198, v198
	s_nop 0
	v_add_f32_e32 v198, 1.0, v198
	v_cmp_gt_f32_e32 vcc, s47, v198
	s_nop 1
	v_cndmask_b32_e64 v200, 0, 32, vcc
	v_ldexp_f32 v198, v198, v200
	v_log_f32_e32 v198, v198
	s_nop 0
	v_mul_f32_e32 v200, 0x3f317217, v198
	v_fma_f32 v200, v198, s94, -v200
	v_fmac_f32_e32 v200, 0x3377d1cf, v198
	v_fmac_f32_e32 v200, 0x3f317217, v198
	v_cmp_lt_f32_e64 s[24:25], |v198|, s51
	s_nop 1
	v_cndmask_b32_e64 v198, v198, v200, s[24:25]
	v_cndmask_b32_e32 v200, 0, v194, vcc
	v_sub_f32_e32 v198, v198, v200
	v_add_f32_e32 v200, v199, v198
	v_lshlrev_b64 v[198:199], 6, v[186:187]
	v_lshl_add_u64 v[198:199], s[42:43], 0, v[198:199]
	v_lshl_add_u64 v[198:199], v[170:171], 2, v[198:199]
	v_add_co_u32_e32 v198, vcc, 0xffffffa0, v198
	s_nop 1
	v_addc_co_u32_e32 v199, vcc, -1, v199, vcc
	flat_store_dword v[198:199], v200
	s_andn2_saveexec_b64 s[24:25], s[92:93]
	s_cbranch_execnz .LBB0_940

; DI float softplus_fast(float x) { return fmaxf(x, 0.f) + __logf(1.f + __expf(-fabsf(x))); }
.LBB0_926:
	v_lshl_add_u64 v[198:199], v[152:153], 2, s[28:29]
	v_mov_b32_e32 v198, v231
	v_add_f32_e32 v198, v103, v198
	v_max_f32_e32 v199, 0, v198
	v_mul_f32_e64 v198, |v198|, s46
	v_exp_f32_e32 v198, v198
	s_nop 0
	v_add_f32_e32 v198, 1.0, v198
	v_cmp_gt_f32_e32 vcc, s47, v198
	s_nop 1
	v_cndmask_b32_e64 v200, 0, 32, vcc
	v_ldexp_f32 v198, v198, v200
	v_log_f32_e32 v198, v198
	s_nop 0
	v_mul_f32_e32 v200, 0x3f317217, v198
	v_fma_f32 v200, v198, s94, -v200
	v_fmac_f32_e32 v200, 0x3377d1cf, v198
	v_fmac_f32_e32 v200, 0x3f317217, v198
	v_cmp_lt_f32_e64 s[24:25], |v198|, s51
	s_nop 1
	v_cndmask_b32_e64 v198, v198, v200, s[24:25]
	v_cndmask_b32_e32 v200, 0, v194, vcc
	v_sub_f32_e32 v198, v198, v200
	v_add_f32_e32 v200, v199, v198
	v_lshlrev_b64 v[198:199], 6, v[186:187]
	v_lshl_add_u64 v[198:199], s[42:43], 0, v[198:199]
	v_lshl_add_u64 v[198:199], v[166:167], 2, v[198:199]
	v_add_co_u32_e32 v198, vcc, 0xffffffa0, v198
	s_nop 1
	v_addc_co_u32_e32 v199, vcc, -1, v199, vcc
	flat_store_dword v[198:199], v200
	s_andn2_saveexec_b64 s[24:25], s[92:93]
	s_cbranch_execnz .LBB0_942

; DI float softplus_fast(float x) { return fmaxf(x, 0.f) + __logf(1.f + __expf(-fabsf(x))); }
.LBB0_928:
	v_lshl_add_u64 v[198:199], v[152:153], 2, s[28:29]
	v_mov_b32_e32 v198, v232
	v_add_f32_e32 v198, v96, v198
	v_max_f32_e32 v199, 0, v198
	v_mul_f32_e64 v198, |v198|, s46
	v_exp_f32_e32 v198, v198
	s_nop 0
	v_add_f32_e32 v198, 1.0, v198
	v_cmp_gt_f32_e32 vcc, s47, v198
	s_nop 1
	v_cndmask_b32_e64 v200, 0, 32, vcc
	v_ldexp_f32 v198, v198, v200
	v_log_f32_e32 v198, v198
	s_nop 0
	v_mul_f32_e32 v200, 0x3f317217, v198
	v_fma_f32 v200, v198, s94, -v200
	v_fmac_f32_e32 v200, 0x3377d1cf, v198
	v_fmac_f32_e32 v200, 0x3f317217, v198
	v_cmp_lt_f32_e64 s[24:25], |v198|, s51
	s_nop 1
	v_cndmask_b32_e64 v198, v198, v200, s[24:25]
	v_cndmask_b32_e32 v200, 0, v194, vcc
	v_sub_f32_e32 v198, v198, v200
	v_add_f32_e32 v200, v199, v198
	v_lshlrev_b64 v[198:199], 6, v[186:187]
	v_lshl_add_u64 v[198:199], s[42:43], 0, v[198:199]
	v_lshl_add_u64 v[198:199], v[162:163], 2, v[198:199]
	v_add_co_u32_e32 v198, vcc, 0xffffffa0, v198
	s_nop 1
	v_addc_co_u32_e32 v199, vcc, -1, v199, vcc
	flat_store_dword v[198:199], v200
	s_andn2_saveexec_b64 s[24:25], s[92:93]
	s_cbranch_execnz .LBB0_944

; DI float softplus_fast(float x) { return fmaxf(x, 0.f) + __logf(1.f + __expf(-fabsf(x))); }
.LBB0_930:
	v_lshl_add_u64 v[198:199], v[152:153], 2, s[28:29]
	v_mov_b32_e32 v198, v233
	v_add_f32_e32 v198, v97, v198
	v_max_f32_e32 v199, 0, v198
	v_mul_f32_e64 v198, |v198|, s46
	v_exp_f32_e32 v198, v198
	s_nop 0
	v_add_f32_e32 v198, 1.0, v198
	v_cmp_gt_f32_e32 vcc, s47, v198
	s_nop 1
	v_cndmask_b32_e64 v200, 0, 32, vcc
	v_ldexp_f32 v198, v198, v200
	v_log_f32_e32 v198, v198
	s_nop 0
	v_mul_f32_e32 v200, 0x3f317217, v198
	v_fma_f32 v200, v198, s94, -v200
	v_fmac_f32_e32 v200, 0x3377d1cf, v198
	v_fmac_f32_e32 v200, 0x3f317217, v198
	v_cmp_lt_f32_e64 s[24:25], |v198|, s51
	s_nop 1
	v_cndmask_b32_e64 v198, v198, v200, s[24:25]
	v_cndmask_b32_e32 v200, 0, v194, vcc
	v_sub_f32_e32 v198, v198, v200
	v_add_f32_e32 v200, v199, v198
	v_lshlrev_b64 v[198:199], 6, v[186:187]
	v_lshl_add_u64 v[198:199], s[42:43], 0, v[198:199]
	v_lshl_add_u64 v[198:199], v[140:141], 2, v[198:199]
	v_add_co_u32_e32 v198, vcc, 0xffffffa0, v198
	s_nop 1
	v_addc_co_u32_e32 v199, vcc, -1, v199, vcc
	flat_store_dword v[198:199], v200
	s_andn2_saveexec_b64 s[24:25], s[92:93]
	s_cbranch_execnz .LBB0_946

; DI float softplus_fast(float x) { return fmaxf(x, 0.f) + __logf(1.f + __expf(-fabsf(x))); }
.LBB0_932:
	v_lshl_add_u64 v[198:199], v[152:153], 2, s[28:29]
	v_mov_b32_e32 v198, v234
	v_add_f32_e32 v198, v98, v198
	v_max_f32_e32 v199, 0, v198
	v_mul_f32_e64 v198, |v198|, s46
	v_exp_f32_e32 v198, v198
	s_nop 0
	v_add_f32_e32 v198, 1.0, v198
	v_cmp_gt_f32_e32 vcc, s47, v198
	s_nop 1
	v_cndmask_b32_e64 v200, 0, 32, vcc
	v_ldexp_f32 v198, v198, v200
	v_log_f32_e32 v198, v198
	s_nop 0
	v_mul_f32_e32 v200, 0x3f317217, v198
	v_fma_f32 v200, v198, s94, -v200
	v_fmac_f32_e32 v200, 0x3377d1cf, v198
	v_fmac_f32_e32 v200, 0x3f317217, v198
	v_cmp_lt_f32_e64 s[24:25], |v198|, s51
	s_nop 1
	v_cndmask_b32_e64 v198, v198, v200, s[24:25]
	v_cndmask_b32_e32 v200, 0, v194, vcc
	v_sub_f32_e32 v198, v198, v200
	v_add_f32_e32 v200, v199, v198
	v_lshlrev_b64 v[198:199], 6, v[186:187]
	v_lshl_add_u64 v[198:199], s[42:43], 0, v[198:199]
	v_lshl_add_u64 v[198:199], v[136:137], 2, v[198:199]
	v_add_co_u32_e32 v198, vcc, 0xffffffa0, v198
	s_nop 1
	v_addc_co_u32_e32 v199, vcc, -1, v199, vcc
	flat_store_dword v[198:199], v200
	s_andn2_saveexec_b64 s[24:25], s[92:93]
	s_cbranch_execnz .LBB0_948

; DI float softplus_fast(float x) { return fmaxf(x, 0.f) + __logf(1.f + __expf(-fabsf(x))); }
.LBB0_934:
	v_lshl_add_u64 v[198:199], v[152:153], 2, s[28:29]
	v_mov_b32_e32 v198, v235
	v_lshlrev_b64 v[186:187], 6, v[186:187]
	v_lshl_add_u64 v[186:187], s[42:43], 0, v[186:187]
	v_lshl_add_u64 v[186:187], v[132:133], 2, v[186:187]
	v_add_f32_e32 v198, v99, v198
	v_max_f32_e32 v199, 0, v198
	v_mul_f32_e64 v198, |v198|, s46
	v_exp_f32_e32 v198, v198
	s_nop 0
	v_add_f32_e32 v198, 1.0, v198
	v_cmp_gt_f32_e32 vcc, s47, v198
	s_nop 1
	v_cndmask_b32_e64 v200, 0, 32, vcc
	v_ldexp_f32 v198, v198, v200
	v_log_f32_e32 v198, v198
	s_nop 0
	v_mul_f32_e32 v200, 0x3f317217, v198
	v_fma_f32 v200, v198, s94, -v200
	v_fmac_f32_e32 v200, 0x3377d1cf, v198
	v_fmac_f32_e32 v200, 0x3f317217, v198
	v_cmp_lt_f32_e64 s[24:25], |v198|, s51
	s_nop 1
	v_cndmask_b32_e64 v198, v198, v200, s[24:25]
	v_cndmask_b32_e32 v200, 0, v194, vcc
	v_sub_f32_e32 v198, v198, v200
	v_add_co_u32_e32 v186, vcc, 0xffffffa0, v186
	v_add_f32_e32 v198, v199, v198
	s_nop 0
	v_addc_co_u32_e32 v187, vcc, -1, v187, vcc
	flat_store_dword v[186:187], v198
	s_andn2_saveexec_b64 s[24:25], s[92:93]
	s_cbranch_execnz .LBB0_950
	s_branch .LBB0_951

; #define TS_(e) { const unsigned w0_ = pk2(ta0[e], ta1[e]); vt[(size_t)(e) * SEQ] = (bf16_t)(w0_ & 0xffff); vt[(size_t)((e) + 4) * SEQ] = (bf16_t)(w0_ >> 16); }
; #define GV_(n, e) { const int c_ = cb + 4 * (n) + (e); const float v_ = (n) ? tb1[e] : tb0[e]; if (c_ < 24) GATES[(size_t)row * 24 + c_] = sigmoidf_(v_); else if (c_ < 40) DT[(size_t)row * 16 + c_ - 24] = softplus_fast(v_ + dt_bias[c_ - 24]); }
;     DI void operator()(const Acc& acc, const Unit& u, int wr, int wc, int fr, int fq) const {
;     ...
;                 else { bf16_t* vt = VWT + ((size_t)(b * 2 + h) * 64 + d0) * SEQ + t; const f32x4 ta0 = acc[ai][0][m][0], ta1 = acc[ai][0][m][1]; TS_(0) TS_(1) TS_(2) TS_(3)
;                   const int cb = wc * 32 + 8 * fq; const f32x4 tb0 = acc[ai][1][m][0], tb1 = acc[ai][1][m][1];
;                   if (cb < 40) { GV_(0, 0) GV_(0, 1) GV_(0, 2) GV_(0, 3) GV_(1, 0) GV_(1, 1) GV_(1, 2) GV_(1, 3) } } )
.LBB0_954:
	v_add_u32_e32 v186, 32, v182
	v_and_b32_e32 v183, 0x1fff, v186
	v_ashrrev_i32_e32 v197, 13, v186
	s_and_b64 vcc, exec, s[22:23]
	s_mov_b64 s[24:25], -1
	s_cbranch_vccnz .LBB0_989
	v_lshl_or_b32 v198, v197, 1, s63
	v_ashrrev_i32_e32 v199, 31, v198
	v_lshlrev_b64 v[198:199], 20, v[198:199]
	v_lshl_add_u64 v[198:199], v[180:181], 0, v[198:199]
	v_lshlrev_b32_e32 v200, 1, v183
	v_mov_b32_e32 v201, v153
	v_lshl_add_u64 v[198:199], v[198:199], 0, v[200:201]
	v_add_co_u32_e32 v200, vcc, 0x10000, v198
	v_cvt_pk_bf16_f32 v187, v92, v88
	s_nop 0
	v_addc_co_u32_e32 v201, vcc, 0, v199, vcc
	flat_store_short_d16_hi v[200:201], v187
	v_add_co_u32_e32 v200, vcc, 0x4000, v198
	flat_store_short v[198:199], v187
	v_cvt_pk_bf16_f32 v187, v93, v89
	v_addc_co_u32_e32 v201, vcc, 0, v199, vcc
	flat_store_short v[200:201], v187
	v_add_co_u32_e32 v200, vcc, 0x14000, v198
	s_nop 1
	v_addc_co_u32_e32 v201, vcc, 0, v199, vcc
	flat_store_short_d16_hi v[200:201], v187
	v_add_co_u32_e32 v200, vcc, 0x8000, v198
	v_cvt_pk_bf16_f32 v187, v94, v90
	s_nop 0
	v_addc_co_u32_e32 v201, vcc, 0, v199, vcc
	flat_store_short v[200:201], v187
	v_add_co_u32_e32 v200, vcc, 0x18000, v198
	s_nop 1
	v_addc_co_u32_e32 v201, vcc, 0, v199, vcc
	flat_store_short_d16_hi v[200:201], v187
	v_add_co_u32_e32 v200, vcc, 0xc000, v198
	v_cvt_pk_bf16_f32 v187, v95, v91
	s_nop 0
	v_addc_co_u32_e32 v201, vcc, 0, v199, vcc
	v_add_co_u32_e32 v198, vcc, 0x1c000, v198
	flat_store_short v[200:201], v187
	s_nop 0
	v_addc_co_u32_e32 v199, vcc, 0, v199, vcc
	flat_store_short_d16_hi v[198:199], v187
	s_and_saveexec_b64 s[90:91], s[20:21]
	s_cbranch_execz .LBB0_988
	v_ashrrev_i32_e32 v187, 31, v186
	s_and_saveexec_b64 s[24:25], s[18:19]
	s_xor_b64 s[92:93], exec, s[24:25]
	s_cbranch_execz .LBB0_972
	v_lshl_add_u64 v[198:199], v[152:153], 2, s[28:29]
	v_mov_b32_e32 v198, v228
	v_add_f32_e32 v198, v84, v198
	v_max_f32_e32 v199, 0, v198
	v_mul_f32_e64 v198, |v198|, s46
	v_exp_f32_e32 v198, v198
	s_nop 0
	v_add_f32_e32 v198, 1.0, v198
	v_cmp_gt_f32_e32 vcc, s47, v198
	s_nop 1
	v_cndmask_b32_e64 v200, 0, 32, vcc
	v_ldexp_f32 v198, v198, v200
	v_log_f32_e32 v198, v198
	s_nop 0
	v_mul_f32_e32 v200, 0x3f317217, v198
	v_fma_f32 v200, v198, s94, -v200
	v_fmac_f32_e32 v200, 0x3377d1cf, v198
	v_fmac_f32_e32 v200, 0x3f317217, v198
	v_cmp_lt_f32_e64 s[24:25], |v198|, s51
	s_nop 1
	v_cndmask_b32_e64 v198, v198, v200, s[24:25]
	v_cndmask_b32_e32 v200, 0, v194, vcc
	v_sub_f32_e32 v198, v198, v200
	v_add_f32_e32 v200, v199, v198
	v_lshlrev_b64 v[198:199], 6, v[186:187]
	v_lshl_add_u64 v[198:199], v[176:177], 0, v[198:199]
	v_add_co_u32_e32 v198, vcc, 0xffffffa0, v198
	s_nop 1
	v_addc_co_u32_e32 v199, vcc, -1, v199, vcc
	flat_store_dword v[198:199], v200
	s_andn2_saveexec_b64 s[24:25], s[92:93]
	s_cbranch_execnz .LBB0_973

; DI float softplus_fast(float x) { return fmaxf(x, 0.f) + __logf(1.f + __expf(-fabsf(x))); }
.LBB0_959:
	v_lshl_add_u64 v[198:199], v[152:153], 2, s[28:29]
	v_mov_b32_e32 v198, v229
	v_add_f32_e32 v198, v85, v198
	v_max_f32_e32 v199, 0, v198
	v_mul_f32_e64 v198, |v198|, s46
	v_exp_f32_e32 v198, v198
	s_nop 0
	v_add_f32_e32 v198, 1.0, v198
	v_cmp_gt_f32_e32 vcc, s47, v198
	s_nop 1
	v_cndmask_b32_e64 v200, 0, 32, vcc
	v_ldexp_f32 v198, v198, v200
	v_log_f32_e32 v198, v198
	s_nop 0
	v_mul_f32_e32 v200, 0x3f317217, v198
	v_fma_f32 v200, v198, s94, -v200
	v_fmac_f32_e32 v200, 0x3377d1cf, v198
	v_fmac_f32_e32 v200, 0x3f317217, v198
	v_cmp_lt_f32_e64 s[24:25], |v198|, s51
	s_nop 1
	v_cndmask_b32_e64 v198, v198, v200, s[24:25]
	v_cndmask_b32_e32 v200, 0, v194, vcc
	v_sub_f32_e32 v198, v198, v200
	v_add_f32_e32 v200, v199, v198
	v_lshlrev_b64 v[198:199], 6, v[186:187]
	v_lshl_add_u64 v[198:199], s[42:43], 0, v[198:199]
	v_lshl_add_u64 v[198:199], v[174:175], 2, v[198:199]
	v_add_co_u32_e32 v198, vcc, 0xffffffa0, v198
	s_nop 1
	v_addc_co_u32_e32 v199, vcc, -1, v199, vcc
	flat_store_dword v[198:199], v200
	s_andn2_saveexec_b64 s[24:25], s[92:93]
	s_cbranch_execnz .LBB0_975

; DI float softplus_fast(float x) { return fmaxf(x, 0.f) + __logf(1.f + __expf(-fabsf(x))); }
.LBB0_961:
	v_lshl_add_u64 v[198:199], v[152:153], 2, s[28:29]
	v_mov_b32_e32 v198, v230
	v_add_f32_e32 v198, v86, v198
	v_max_f32_e32 v199, 0, v198
	v_mul_f32_e64 v198, |v198|, s46
	v_exp_f32_e32 v198, v198
	s_nop 0
	v_add_f32_e32 v198, 1.0, v198
	v_cmp_gt_f32_e32 vcc, s47, v198
	s_nop 1
	v_cndmask_b32_e64 v200, 0, 32, vcc
	v_ldexp_f32 v198, v198, v200
	v_log_f32_e32 v198, v198
	s_nop 0
	v_mul_f32_e32 v200, 0x3f317217, v198
	v_fma_f32 v200, v198, s94, -v200
	v_fmac_f32_e32 v200, 0x3377d1cf, v198
	v_fmac_f32_e32 v200, 0x3f317217, v198
	v_cmp_lt_f32_e64 s[24:25], |v198|, s51
	s_nop 1
	v_cndmask_b32_e64 v198, v198, v200, s[24:25]
	v_cndmask_b32_e32 v200, 0, v194, vcc
	v_sub_f32_e32 v198, v198, v200
	v_add_f32_e32 v200, v199, v198
	v_lshlrev_b64 v[198:199], 6, v[186:187]
	v_lshl_add_u64 v[198:199], s[42:43], 0, v[198:199]
	v_lshl_add_u64 v[198:199], v[170:171], 2, v[198:199]
	v_add_co_u32_e32 v198, vcc, 0xffffffa0, v198
	s_nop 1
	v_addc_co_u32_e32 v199, vcc, -1, v199, vcc
	flat_store_dword v[198:199], v200
	s_andn2_saveexec_b64 s[24:25], s[92:93]
	s_cbranch_execnz .LBB0_977

; DI float softplus_fast(float x) { return fmaxf(x, 0.f) + __logf(1.f + __expf(-fabsf(x))); }
.LBB0_963:
	v_lshl_add_u64 v[198:199], v[152:153], 2, s[28:29]
	v_mov_b32_e32 v198, v231
	v_add_f32_e32 v198, v87, v198
	v_max_f32_e32 v199, 0, v198
	v_mul_f32_e64 v198, |v198|, s46
	v_exp_f32_e32 v198, v198
	s_nop 0
	v_add_f32_e32 v198, 1.0, v198
	v_cmp_gt_f32_e32 vcc, s47, v198
	s_nop 1
	v_cndmask_b32_e64 v200, 0, 32, vcc
	v_ldexp_f32 v198, v198, v200
	v_log_f32_e32 v198, v198
	s_nop 0
	v_mul_f32_e32 v200, 0x3f317217, v198
	v_fma_f32 v200, v198, s94, -v200
	v_fmac_f32_e32 v200, 0x3377d1cf, v198
	v_fmac_f32_e32 v200, 0x3f317217, v198
	v_cmp_lt_f32_e64 s[24:25], |v198|, s51
	s_nop 1
	v_cndmask_b32_e64 v198, v198, v200, s[24:25]
	v_cndmask_b32_e32 v200, 0, v194, vcc
	v_sub_f32_e32 v198, v198, v200
	v_add_f32_e32 v200, v199, v198
	v_lshlrev_b64 v[198:199], 6, v[186:187]
	v_lshl_add_u64 v[198:199], s[42:43], 0, v[198:199]
	v_lshl_add_u64 v[198:199], v[166:167], 2, v[198:199]
	v_add_co_u32_e32 v198, vcc, 0xffffffa0, v198
	s_nop 1
	v_addc_co_u32_e32 v199, vcc, -1, v199, vcc
	flat_store_dword v[198:199], v200
	s_andn2_saveexec_b64 s[24:25], s[92:93]
	s_cbranch_execnz .LBB0_979

; DI float softplus_fast(float x) { return fmaxf(x, 0.f) + __logf(1.f + __expf(-fabsf(x))); }
.LBB0_965:
	v_lshl_add_u64 v[198:199], v[152:153], 2, s[28:29]
	v_mov_b32_e32 v198, v232
	v_add_f32_e32 v198, v80, v198
	v_max_f32_e32 v199, 0, v198
	v_mul_f32_e64 v198, |v198|, s46
	v_exp_f32_e32 v198, v198
	s_nop 0
	v_add_f32_e32 v198, 1.0, v198
	v_cmp_gt_f32_e32 vcc, s47, v198
	s_nop 1
	v_cndmask_b32_e64 v200, 0, 32, vcc
	v_ldexp_f32 v198, v198, v200
	v_log_f32_e32 v198, v198
	s_nop 0
	v_mul_f32_e32 v200, 0x3f317217, v198
	v_fma_f32 v200, v198, s94, -v200
	v_fmac_f32_e32 v200, 0x3377d1cf, v198
	v_fmac_f32_e32 v200, 0x3f317217, v198
	v_cmp_lt_f32_e64 s[24:25], |v198|, s51
	s_nop 1
	v_cndmask_b32_e64 v198, v198, v200, s[24:25]
	v_cndmask_b32_e32 v200, 0, v194, vcc
	v_sub_f32_e32 v198, v198, v200
	v_add_f32_e32 v200, v199, v198
	v_lshlrev_b64 v[198:199], 6, v[186:187]
	v_lshl_add_u64 v[198:199], s[42:43], 0, v[198:199]
	v_lshl_add_u64 v[198:199], v[162:163], 2, v[198:199]
	v_add_co_u32_e32 v198, vcc, 0xffffffa0, v198
	s_nop 1
	v_addc_co_u32_e32 v199, vcc, -1, v199, vcc
	flat_store_dword v[198:199], v200
	s_andn2_saveexec_b64 s[24:25], s[92:93]
	s_cbranch_execnz .LBB0_981

; DI float softplus_fast(float x) { return fmaxf(x, 0.f) + __logf(1.f + __expf(-fabsf(x))); }
.LBB0_967:
	v_lshl_add_u64 v[198:199], v[152:153], 2, s[28:29]
	v_mov_b32_e32 v198, v233
	v_add_f32_e32 v198, v81, v198
	v_max_f32_e32 v199, 0, v198
	v_mul_f32_e64 v198, |v198|, s46
	v_exp_f32_e32 v198, v198
	s_nop 0
	v_add_f32_e32 v198, 1.0, v198
	v_cmp_gt_f32_e32 vcc, s47, v198
	s_nop 1
	v_cndmask_b32_e64 v200, 0, 32, vcc
	v_ldexp_f32 v198, v198, v200
	v_log_f32_e32 v198, v198
	s_nop 0
	v_mul_f32_e32 v200, 0x3f317217, v198
	v_fma_f32 v200, v198, s94, -v200
	v_fmac_f32_e32 v200, 0x3377d1cf, v198
	v_fmac_f32_e32 v200, 0x3f317217, v198
	v_cmp_lt_f32_e64 s[24:25], |v198|, s51
	s_nop 1
	v_cndmask_b32_e64 v198, v198, v200, s[24:25]
	v_cndmask_b32_e32 v200, 0, v194, vcc
	v_sub_f32_e32 v198, v198, v200
	v_add_f32_e32 v200, v199, v198
	v_lshlrev_b64 v[198:199], 6, v[186:187]
	v_lshl_add_u64 v[198:199], s[42:43], 0, v[198:199]
	v_lshl_add_u64 v[198:199], v[140:141], 2, v[198:199]
	v_add_co_u32_e32 v198, vcc, 0xffffffa0, v198
	s_nop 1
	v_addc_co_u32_e32 v199, vcc, -1, v199, vcc
	flat_store_dword v[198:199], v200
	s_andn2_saveexec_b64 s[24:25], s[92:93]
	s_cbranch_execnz .LBB0_983

; DI float softplus_fast(float x) { return fmaxf(x, 0.f) + __logf(1.f + __expf(-fabsf(x))); }
.LBB0_969:
	v_lshl_add_u64 v[198:199], v[152:153], 2, s[28:29]
	v_mov_b32_e32 v198, v234
	v_add_f32_e32 v198, v82, v198
	v_max_f32_e32 v199, 0, v198
	v_mul_f32_e64 v198, |v198|, s46
	v_exp_f32_e32 v198, v198
	s_nop 0
	v_add_f32_e32 v198, 1.0, v198
	v_cmp_gt_f32_e32 vcc, s47, v198
	s_nop 1
	v_cndmask_b32_e64 v200, 0, 32, vcc
	v_ldexp_f32 v198, v198, v200
	v_log_f32_e32 v198, v198
	s_nop 0
	v_mul_f32_e32 v200, 0x3f317217, v198
	v_fma_f32 v200, v198, s94, -v200
	v_fmac_f32_e32 v200, 0x3377d1cf, v198
	v_fmac_f32_e32 v200, 0x3f317217, v198
	v_cmp_lt_f32_e64 s[24:25], |v198|, s51
	s_nop 1
	v_cndmask_b32_e64 v198, v198, v200, s[24:25]
	v_cndmask_b32_e32 v200, 0, v194, vcc
	v_sub_f32_e32 v198, v198, v200
	v_add_f32_e32 v200, v199, v198
	v_lshlrev_b64 v[198:199], 6, v[186:187]
	v_lshl_add_u64 v[198:199], s[42:43], 0, v[198:199]
	v_lshl_add_u64 v[198:199], v[136:137], 2, v[198:199]
	v_add_co_u32_e32 v198, vcc, 0xffffffa0, v198
	s_nop 1
	v_addc_co_u32_e32 v199, vcc, -1, v199, vcc
	flat_store_dword v[198:199], v200
	s_andn2_saveexec_b64 s[24:25], s[92:93]
	s_cbranch_execnz .LBB0_985

; DI float softplus_fast(float x) { return fmaxf(x, 0.f) + __logf(1.f + __expf(-fabsf(x))); }
.LBB0_971:
	v_lshl_add_u64 v[198:199], v[152:153], 2, s[28:29]
	v_mov_b32_e32 v198, v235
	v_lshlrev_b64 v[186:187], 6, v[186:187]
	v_lshl_add_u64 v[186:187], s[42:43], 0, v[186:187]
	v_lshl_add_u64 v[186:187], v[132:133], 2, v[186:187]
	v_add_f32_e32 v198, v83, v198
	v_max_f32_e32 v199, 0, v198
	v_mul_f32_e64 v198, |v198|, s46
	v_exp_f32_e32 v198, v198
	s_nop 0
	v_add_f32_e32 v198, 1.0, v198
	v_cmp_gt_f32_e32 vcc, s47, v198
	s_nop 1
	v_cndmask_b32_e64 v200, 0, 32, vcc
	v_ldexp_f32 v198, v198, v200
	v_log_f32_e32 v198, v198
	s_nop 0
	v_mul_f32_e32 v200, 0x3f317217, v198
	v_fma_f32 v200, v198, s94, -v200
	v_fmac_f32_e32 v200, 0x3377d1cf, v198
	v_fmac_f32_e32 v200, 0x3f317217, v198
	v_cmp_lt_f32_e64 s[24:25], |v198|, s51
	s_nop 1
	v_cndmask_b32_e64 v198, v198, v200, s[24:25]
	v_cndmask_b32_e32 v200, 0, v194, vcc
	v_sub_f32_e32 v198, v198, v200
	v_add_co_u32_e32 v186, vcc, 0xffffffa0, v186
	v_add_f32_e32 v198, v199, v198
	s_nop 0
	v_addc_co_u32_e32 v187, vcc, -1, v187, vcc
	flat_store_dword v[186:187], v198
	s_andn2_saveexec_b64 s[24:25], s[92:93]
	s_cbranch_execnz .LBB0_987
	s_branch .LBB0_988

; #define TS_(e) { const unsigned w0_ = pk2(ta0[e], ta1[e]); vt[(size_t)(e) * SEQ] = (bf16_t)(w0_ & 0xffff); vt[(size_t)((e) + 4) * SEQ] = (bf16_t)(w0_ >> 16); }
; #define GV_(n, e) { const int c_ = cb + 4 * (n) + (e); const float v_ = (n) ? tb1[e] : tb0[e]; if (c_ < 24) GATES[(size_t)row * 24 + c_] = sigmoidf_(v_); else if (c_ < 40) DT[(size_t)row * 16 + c_ - 24] = softplus_fast(v_ + dt_bias[c_ - 24]); }
;     DI void operator()(const Acc& acc, const Unit& u, int wr, int wc, int fr, int fq) const {
;     ...
;                 else { bf16_t* vt = VWT + ((size_t)(b * 2 + h) * 64 + d0) * SEQ + t; const f32x4 ta0 = acc[ai][0][m][0], ta1 = acc[ai][0][m][1]; TS_(0) TS_(1) TS_(2) TS_(3)
;                   const int cb = wc * 32 + 8 * fq; const f32x4 tb0 = acc[ai][1][m][0], tb1 = acc[ai][1][m][1];
;                   if (cb < 40) { GV_(0, 0) GV_(0, 1) GV_(0, 2) GV_(0, 3) GV_(1, 0) GV_(1, 1) GV_(1, 2) GV_(1, 3) } } )
.LBB0_991:
	v_add_u32_e32 v186, 48, v182
	v_and_b32_e32 v183, 0x1fff, v186
	v_ashrrev_i32_e32 v197, 13, v186
	s_and_b64 vcc, exec, s[22:23]
	s_mov_b64 s[24:25], -1
	s_cbranch_vccnz .LBB0_1026
	v_lshl_or_b32 v198, v197, 1, s63
	v_ashrrev_i32_e32 v199, 31, v198
	v_lshlrev_b64 v[198:199], 20, v[198:199]
	v_lshl_add_u64 v[198:199], v[180:181], 0, v[198:199]
	v_lshlrev_b32_e32 v200, 1, v183
	v_mov_b32_e32 v201, v153
	v_lshl_add_u64 v[198:199], v[198:199], 0, v[200:201]
	v_add_co_u32_e32 v200, vcc, 0x10000, v198
	v_cvt_pk_bf16_f32 v187, v76, v72
	s_nop 0
	v_addc_co_u32_e32 v201, vcc, 0, v199, vcc
	flat_store_short_d16_hi v[200:201], v187
	v_add_co_u32_e32 v200, vcc, 0x4000, v198
	flat_store_short v[198:199], v187
	v_cvt_pk_bf16_f32 v187, v77, v73
	v_addc_co_u32_e32 v201, vcc, 0, v199, vcc
	flat_store_short v[200:201], v187
	v_add_co_u32_e32 v200, vcc, 0x14000, v198
	s_nop 1
	v_addc_co_u32_e32 v201, vcc, 0, v199, vcc
	flat_store_short_d16_hi v[200:201], v187
	v_add_co_u32_e32 v200, vcc, 0x8000, v198
	v_cvt_pk_bf16_f32 v187, v78, v74
	s_nop 0
	v_addc_co_u32_e32 v201, vcc, 0, v199, vcc
	flat_store_short v[200:201], v187
	v_add_co_u32_e32 v200, vcc, 0x18000, v198
	s_nop 1
	v_addc_co_u32_e32 v201, vcc, 0, v199, vcc
	flat_store_short_d16_hi v[200:201], v187
	v_add_co_u32_e32 v200, vcc, 0xc000, v198
	v_cvt_pk_bf16_f32 v187, v79, v75
	s_nop 0
	v_addc_co_u32_e32 v201, vcc, 0, v199, vcc
	v_add_co_u32_e32 v198, vcc, 0x1c000, v198
	flat_store_short v[200:201], v187
	s_nop 0
	v_addc_co_u32_e32 v199, vcc, 0, v199, vcc
	flat_store_short_d16_hi v[198:199], v187
	s_and_saveexec_b64 s[90:91], s[20:21]
	s_cbranch_execz .LBB0_1025
	v_ashrrev_i32_e32 v187, 31, v186
	s_and_saveexec_b64 s[24:25], s[18:19]
	s_xor_b64 s[92:93], exec, s[24:25]
	s_cbranch_execz .LBB0_1009
	v_lshl_add_u64 v[198:199], v[152:153], 2, s[28:29]
	v_mov_b32_e32 v198, v228
	v_add_f32_e32 v198, v68, v198
	v_max_f32_e32 v199, 0, v198
	v_mul_f32_e64 v198, |v198|, s46
	v_exp_f32_e32 v198, v198
	s_nop 0
	v_add_f32_e32 v198, 1.0, v198
	v_cmp_gt_f32_e32 vcc, s47, v198
	s_nop 1
	v_cndmask_b32_e64 v200, 0, 32, vcc
	v_ldexp_f32 v198, v198, v200
	v_log_f32_e32 v198, v198
	s_nop 0
	v_mul_f32_e32 v200, 0x3f317217, v198
	v_fma_f32 v200, v198, s94, -v200
	v_fmac_f32_e32 v200, 0x3377d1cf, v198
	v_fmac_f32_e32 v200, 0x3f317217, v198
	v_cmp_lt_f32_e64 s[24:25], |v198|, s51
	s_nop 1
	v_cndmask_b32_e64 v198, v198, v200, s[24:25]
	v_cndmask_b32_e32 v200, 0, v194, vcc
	v_sub_f32_e32 v198, v198, v200
	v_add_f32_e32 v200, v199, v198
	v_lshlrev_b64 v[198:199], 6, v[186:187]
	v_lshl_add_u64 v[198:199], v[176:177], 0, v[198:199]
	v_add_co_u32_e32 v198, vcc, 0xffffffa0, v198
	s_nop 1
	v_addc_co_u32_e32 v199, vcc, -1, v199, vcc
	flat_store_dword v[198:199], v200
	s_andn2_saveexec_b64 s[24:25], s[92:93]
	s_cbranch_execnz .LBB0_1010

; DI float softplus_fast(float x) { return fmaxf(x, 0.f) + __logf(1.f + __expf(-fabsf(x))); }
.LBB0_996:
	v_lshl_add_u64 v[198:199], v[152:153], 2, s[28:29]
	v_mov_b32_e32 v198, v229
	v_add_f32_e32 v198, v69, v198
	v_max_f32_e32 v199, 0, v198
	v_mul_f32_e64 v198, |v198|, s46
	v_exp_f32_e32 v198, v198
	s_nop 0
	v_add_f32_e32 v198, 1.0, v198
	v_cmp_gt_f32_e32 vcc, s47, v198
	s_nop 1
	v_cndmask_b32_e64 v200, 0, 32, vcc
	v_ldexp_f32 v198, v198, v200
	v_log_f32_e32 v198, v198
	s_nop 0
	v_mul_f32_e32 v200, 0x3f317217, v198
	v_fma_f32 v200, v198, s94, -v200
	v_fmac_f32_e32 v200, 0x3377d1cf, v198
	v_fmac_f32_e32 v200, 0x3f317217, v198
	v_cmp_lt_f32_e64 s[24:25], |v198|, s51
	s_nop 1
	v_cndmask_b32_e64 v198, v198, v200, s[24:25]
	v_cndmask_b32_e32 v200, 0, v194, vcc
	v_sub_f32_e32 v198, v198, v200
	v_add_f32_e32 v200, v199, v198
	v_lshlrev_b64 v[198:199], 6, v[186:187]
	v_lshl_add_u64 v[198:199], s[42:43], 0, v[198:199]
	v_lshl_add_u64 v[198:199], v[174:175], 2, v[198:199]
	v_add_co_u32_e32 v198, vcc, 0xffffffa0, v198
	s_nop 1
	v_addc_co_u32_e32 v199, vcc, -1, v199, vcc
	flat_store_dword v[198:199], v200
	s_andn2_saveexec_b64 s[24:25], s[92:93]
	s_cbranch_execnz .LBB0_1012

; DI float softplus_fast(float x) { return fmaxf(x, 0.f) + __logf(1.f + __expf(-fabsf(x))); }
.LBB0_998:
	v_lshl_add_u64 v[198:199], v[152:153], 2, s[28:29]
	v_mov_b32_e32 v198, v230
	v_add_f32_e32 v198, v70, v198
	v_max_f32_e32 v199, 0, v198
	v_mul_f32_e64 v198, |v198|, s46
	v_exp_f32_e32 v198, v198
	s_nop 0
	v_add_f32_e32 v198, 1.0, v198
	v_cmp_gt_f32_e32 vcc, s47, v198
	s_nop 1
	v_cndmask_b32_e64 v200, 0, 32, vcc
	v_ldexp_f32 v198, v198, v200
	v_log_f32_e32 v198, v198
	s_nop 0
	v_mul_f32_e32 v200, 0x3f317217, v198
	v_fma_f32 v200, v198, s94, -v200
	v_fmac_f32_e32 v200, 0x3377d1cf, v198
	v_fmac_f32_e32 v200, 0x3f317217, v198
	v_cmp_lt_f32_e64 s[24:25], |v198|, s51
	s_nop 1
	v_cndmask_b32_e64 v198, v198, v200, s[24:25]
	v_cndmask_b32_e32 v200, 0, v194, vcc
	v_sub_f32_e32 v198, v198, v200
	v_add_f32_e32 v200, v199, v198
	v_lshlrev_b64 v[198:199], 6, v[186:187]
	v_lshl_add_u64 v[198:199], s[42:43], 0, v[198:199]
	v_lshl_add_u64 v[198:199], v[170:171], 2, v[198:199]
	v_add_co_u32_e32 v198, vcc, 0xffffffa0, v198
	s_nop 1
	v_addc_co_u32_e32 v199, vcc, -1, v199, vcc
	flat_store_dword v[198:199], v200
	s_andn2_saveexec_b64 s[24:25], s[92:93]
	s_cbranch_execnz .LBB0_1014

; DI float softplus_fast(float x) { return fmaxf(x, 0.f) + __logf(1.f + __expf(-fabsf(x))); }
.LBB0_1000:
	v_lshl_add_u64 v[198:199], v[152:153], 2, s[28:29]
	v_mov_b32_e32 v198, v231
	v_add_f32_e32 v198, v71, v198
	v_max_f32_e32 v199, 0, v198
	v_mul_f32_e64 v198, |v198|, s46
	v_exp_f32_e32 v198, v198
	s_nop 0
	v_add_f32_e32 v198, 1.0, v198
	v_cmp_gt_f32_e32 vcc, s47, v198
	s_nop 1
	v_cndmask_b32_e64 v200, 0, 32, vcc
	v_ldexp_f32 v198, v198, v200
	v_log_f32_e32 v198, v198
	s_nop 0
	v_mul_f32_e32 v200, 0x3f317217, v198
	v_fma_f32 v200, v198, s94, -v200
	v_fmac_f32_e32 v200, 0x3377d1cf, v198
	v_fmac_f32_e32 v200, 0x3f317217, v198
	v_cmp_lt_f32_e64 s[24:25], |v198|, s51
	s_nop 1
	v_cndmask_b32_e64 v198, v198, v200, s[24:25]
	v_cndmask_b32_e32 v200, 0, v194, vcc
	v_sub_f32_e32 v198, v198, v200
	v_add_f32_e32 v200, v199, v198
	v_lshlrev_b64 v[198:199], 6, v[186:187]
	v_lshl_add_u64 v[198:199], s[42:43], 0, v[198:199]
	v_lshl_add_u64 v[198:199], v[166:167], 2, v[198:199]
	v_add_co_u32_e32 v198, vcc, 0xffffffa0, v198
	s_nop 1
	v_addc_co_u32_e32 v199, vcc, -1, v199, vcc
	flat_store_dword v[198:199], v200
	s_andn2_saveexec_b64 s[24:25], s[92:93]
	s_cbranch_execnz .LBB0_1016

; DI float softplus_fast(float x) { return fmaxf(x, 0.f) + __logf(1.f + __expf(-fabsf(x))); }
.LBB0_1002:
	v_lshl_add_u64 v[198:199], v[152:153], 2, s[28:29]
	v_mov_b32_e32 v198, v232
	v_add_f32_e32 v198, v64, v198
	v_max_f32_e32 v199, 0, v198
	v_mul_f32_e64 v198, |v198|, s46
	v_exp_f32_e32 v198, v198
	s_nop 0
	v_add_f32_e32 v198, 1.0, v198
	v_cmp_gt_f32_e32 vcc, s47, v198
	s_nop 1
	v_cndmask_b32_e64 v200, 0, 32, vcc
	v_ldexp_f32 v198, v198, v200
	v_log_f32_e32 v198, v198
	s_nop 0
	v_mul_f32_e32 v200, 0x3f317217, v198
	v_fma_f32 v200, v198, s94, -v200
	v_fmac_f32_e32 v200, 0x3377d1cf, v198
	v_fmac_f32_e32 v200, 0x3f317217, v198
	v_cmp_lt_f32_e64 s[24:25], |v198|, s51
	s_nop 1
	v_cndmask_b32_e64 v198, v198, v200, s[24:25]
	v_cndmask_b32_e32 v200, 0, v194, vcc
	v_sub_f32_e32 v198, v198, v200
	v_add_f32_e32 v200, v199, v198
	v_lshlrev_b64 v[198:199], 6, v[186:187]
	v_lshl_add_u64 v[198:199], s[42:43], 0, v[198:199]
	v_lshl_add_u64 v[198:199], v[162:163], 2, v[198:199]
	v_add_co_u32_e32 v198, vcc, 0xffffffa0, v198
	s_nop 1
	v_addc_co_u32_e32 v199, vcc, -1, v199, vcc
	flat_store_dword v[198:199], v200
	s_andn2_saveexec_b64 s[24:25], s[92:93]
	s_cbranch_execnz .LBB0_1018

; DI float softplus_fast(float x) { return fmaxf(x, 0.f) + __logf(1.f + __expf(-fabsf(x))); }
.LBB0_1004:
	v_lshl_add_u64 v[198:199], v[152:153], 2, s[28:29]
	v_mov_b32_e32 v198, v233
	v_add_f32_e32 v198, v65, v198
	v_max_f32_e32 v199, 0, v198
	v_mul_f32_e64 v198, |v198|, s46
	v_exp_f32_e32 v198, v198
	s_nop 0
	v_add_f32_e32 v198, 1.0, v198
	v_cmp_gt_f32_e32 vcc, s47, v198
	s_nop 1
	v_cndmask_b32_e64 v200, 0, 32, vcc
	v_ldexp_f32 v198, v198, v200
	v_log_f32_e32 v198, v198
	s_nop 0
	v_mul_f32_e32 v200, 0x3f317217, v198
	v_fma_f32 v200, v198, s94, -v200
	v_fmac_f32_e32 v200, 0x3377d1cf, v198
	v_fmac_f32_e32 v200, 0x3f317217, v198
	v_cmp_lt_f32_e64 s[24:25], |v198|, s51
	s_nop 1
	v_cndmask_b32_e64 v198, v198, v200, s[24:25]
	v_cndmask_b32_e32 v200, 0, v194, vcc
	v_sub_f32_e32 v198, v198, v200
	v_add_f32_e32 v200, v199, v198
	v_lshlrev_b64 v[198:199], 6, v[186:187]
	v_lshl_add_u64 v[198:199], s[42:43], 0, v[198:199]
	v_lshl_add_u64 v[198:199], v[140:141], 2, v[198:199]
	v_add_co_u32_e32 v198, vcc, 0xffffffa0, v198
	s_nop 1
	v_addc_co_u32_e32 v199, vcc, -1, v199, vcc
	flat_store_dword v[198:199], v200
	s_andn2_saveexec_b64 s[24:25], s[92:93]
	s_cbranch_execnz .LBB0_1020

; DI float softplus_fast(float x) { return fmaxf(x, 0.f) + __logf(1.f + __expf(-fabsf(x))); }
.LBB0_1006:
	v_lshl_add_u64 v[198:199], v[152:153], 2, s[28:29]
	v_mov_b32_e32 v198, v234
	v_add_f32_e32 v198, v66, v198
	v_max_f32_e32 v199, 0, v198
	v_mul_f32_e64 v198, |v198|, s46
	v_exp_f32_e32 v198, v198
	s_nop 0
	v_add_f32_e32 v198, 1.0, v198
	v_cmp_gt_f32_e32 vcc, s47, v198
	s_nop 1
	v_cndmask_b32_e64 v200, 0, 32, vcc
	v_ldexp_f32 v198, v198, v200
	v_log_f32_e32 v198, v198
	s_nop 0
	v_mul_f32_e32 v200, 0x3f317217, v198
	v_fma_f32 v200, v198, s94, -v200
	v_fmac_f32_e32 v200, 0x3377d1cf, v198
	v_fmac_f32_e32 v200, 0x3f317217, v198
	v_cmp_lt_f32_e64 s[24:25], |v198|, s51
	s_nop 1
	v_cndmask_b32_e64 v198, v198, v200, s[24:25]
	v_cndmask_b32_e32 v200, 0, v194, vcc
	v_sub_f32_e32 v198, v198, v200
	v_add_f32_e32 v200, v199, v198
	v_lshlrev_b64 v[198:199], 6, v[186:187]
	v_lshl_add_u64 v[198:199], s[42:43], 0, v[198:199]
	v_lshl_add_u64 v[198:199], v[136:137], 2, v[198:199]
	v_add_co_u32_e32 v198, vcc, 0xffffffa0, v198
	s_nop 1
	v_addc_co_u32_e32 v199, vcc, -1, v199, vcc
	flat_store_dword v[198:199], v200
	s_andn2_saveexec_b64 s[24:25], s[92:93]
	s_cbranch_execnz .LBB0_1022

; DI float softplus_fast(float x) { return fmaxf(x, 0.f) + __logf(1.f + __expf(-fabsf(x))); }
.LBB0_1008:
	v_lshl_add_u64 v[198:199], v[152:153], 2, s[28:29]
	v_mov_b32_e32 v198, v235
	v_lshlrev_b64 v[186:187], 6, v[186:187]
	v_lshl_add_u64 v[186:187], s[42:43], 0, v[186:187]
	v_lshl_add_u64 v[186:187], v[132:133], 2, v[186:187]
	v_add_f32_e32 v198, v67, v198
	v_max_f32_e32 v199, 0, v198
	v_mul_f32_e64 v198, |v198|, s46
	v_exp_f32_e32 v198, v198
	s_nop 0
	v_add_f32_e32 v198, 1.0, v198
	v_cmp_gt_f32_e32 vcc, s47, v198
	s_nop 1
	v_cndmask_b32_e64 v200, 0, 32, vcc
	v_ldexp_f32 v198, v198, v200
	v_log_f32_e32 v198, v198
	s_nop 0
	v_mul_f32_e32 v200, 0x3f317217, v198
	v_fma_f32 v200, v198, s94, -v200
	v_fmac_f32_e32 v200, 0x3377d1cf, v198
	v_fmac_f32_e32 v200, 0x3f317217, v198
	v_cmp_lt_f32_e64 s[24:25], |v198|, s51
	s_nop 1
	v_cndmask_b32_e64 v198, v198, v200, s[24:25]
	v_cndmask_b32_e32 v200, 0, v194, vcc
	v_sub_f32_e32 v198, v198, v200
	v_add_co_u32_e32 v186, vcc, 0xffffffa0, v186
	v_add_f32_e32 v198, v199, v198
	s_nop 0
	v_addc_co_u32_e32 v187, vcc, -1, v187, vcc
	flat_store_dword v[186:187], v198
	s_andn2_saveexec_b64 s[24:25], s[92:93]
	s_cbranch_execnz .LBB0_1024
	s_branch .LBB0_1025

; #define TS_(e) { const unsigned w0_ = pk2(ta0[e], ta1[e]); vt[(size_t)(e) * SEQ] = (bf16_t)(w0_ & 0xffff); vt[(size_t)((e) + 4) * SEQ] = (bf16_t)(w0_ >> 16); }
; #define GV_(n, e) { const int c_ = cb + 4 * (n) + (e); const float v_ = (n) ? tb1[e] : tb0[e]; if (c_ < 24) GATES[(size_t)row * 24 + c_] = sigmoidf_(v_); else if (c_ < 40) DT[(size_t)row * 16 + c_ - 24] = softplus_fast(v_ + dt_bias[c_ - 24]); }
;     DI void operator()(const Acc& acc, const Unit& u, int wr, int wc, int fr, int fq) const {
;     ...
;                 else { bf16_t* vt = VWT + ((size_t)(b * 2 + h) * 64 + d0) * SEQ + t; const f32x4 ta0 = acc[ai][0][m][0], ta1 = acc[ai][0][m][1]; TS_(0) TS_(1) TS_(2) TS_(3)
;                   const int cb = wc * 32 + 8 * fq; const f32x4 tb0 = acc[ai][1][m][0], tb1 = acc[ai][1][m][1];
;                   if (cb < 40) { GV_(0, 0) GV_(0, 1) GV_(0, 2) GV_(0, 3) GV_(1, 0) GV_(1, 1) GV_(1, 2) GV_(1, 3) } } )
.LBB0_1028:
	v_add_u32_e32 v186, 0x80, v182
	v_and_b32_e32 v183, 0x1fff, v186
	v_ashrrev_i32_e32 v197, 13, v186
	s_and_b64 vcc, exec, s[22:23]
	s_mov_b64 s[24:25], -1
	s_cbranch_vccnz .LBB0_1063
	v_lshl_or_b32 v198, v197, 1, s63
	v_ashrrev_i32_e32 v199, 31, v198
	v_lshlrev_b64 v[198:199], 20, v[198:199]
	v_lshl_add_u64 v[198:199], v[180:181], 0, v[198:199]
	v_lshlrev_b32_e32 v200, 1, v183
	v_mov_b32_e32 v201, v153
	v_lshl_add_u64 v[198:199], v[198:199], 0, v[200:201]
	v_add_co_u32_e32 v200, vcc, 0x10000, v198
	v_cvt_pk_bf16_f32 v187, v60, v56
	s_nop 0
	v_addc_co_u32_e32 v201, vcc, 0, v199, vcc
	flat_store_short_d16_hi v[200:201], v187
	v_add_co_u32_e32 v200, vcc, 0x4000, v198
	flat_store_short v[198:199], v187
	v_cvt_pk_bf16_f32 v187, v61, v57
	v_addc_co_u32_e32 v201, vcc, 0, v199, vcc
	flat_store_short v[200:201], v187
	v_add_co_u32_e32 v200, vcc, 0x14000, v198
	s_nop 1
	v_addc_co_u32_e32 v201, vcc, 0, v199, vcc
	flat_store_short_d16_hi v[200:201], v187
	v_add_co_u32_e32 v200, vcc, 0x8000, v198
	v_cvt_pk_bf16_f32 v187, v62, v58
	s_nop 0
	v_addc_co_u32_e32 v201, vcc, 0, v199, vcc
	flat_store_short v[200:201], v187
	v_add_co_u32_e32 v200, vcc, 0x18000, v198
	s_nop 1
	v_addc_co_u32_e32 v201, vcc, 0, v199, vcc
	flat_store_short_d16_hi v[200:201], v187
	v_add_co_u32_e32 v200, vcc, 0xc000, v198
	v_cvt_pk_bf16_f32 v187, v63, v59
	s_nop 0
	v_addc_co_u32_e32 v201, vcc, 0, v199, vcc
	v_add_co_u32_e32 v198, vcc, 0x1c000, v198
	flat_store_short v[200:201], v187
	s_nop 0
	v_addc_co_u32_e32 v199, vcc, 0, v199, vcc
	flat_store_short_d16_hi v[198:199], v187
	s_and_saveexec_b64 s[90:91], s[20:21]
	s_cbranch_execz .LBB0_1062
	v_ashrrev_i32_e32 v187, 31, v186
	s_and_saveexec_b64 s[24:25], s[18:19]
	s_xor_b64 s[92:93], exec, s[24:25]
	s_cbranch_execz .LBB0_1046
	v_lshl_add_u64 v[198:199], v[152:153], 2, s[28:29]
	v_mov_b32_e32 v198, v228
	v_add_f32_e32 v198, v52, v198
	v_max_f32_e32 v199, 0, v198
	v_mul_f32_e64 v198, |v198|, s46
	v_exp_f32_e32 v198, v198
	s_nop 0
	v_add_f32_e32 v198, 1.0, v198
	v_cmp_gt_f32_e32 vcc, s47, v198
	s_nop 1
	v_cndmask_b32_e64 v200, 0, 32, vcc
	v_ldexp_f32 v198, v198, v200
	v_log_f32_e32 v198, v198
	s_nop 0
	v_mul_f32_e32 v200, 0x3f317217, v198
	v_fma_f32 v200, v198, s94, -v200
	v_fmac_f32_e32 v200, 0x3377d1cf, v198
	v_fmac_f32_e32 v200, 0x3f317217, v198
	v_cmp_lt_f32_e64 s[24:25], |v198|, s51
	s_nop 1
	v_cndmask_b32_e64 v198, v198, v200, s[24:25]
	v_cndmask_b32_e32 v200, 0, v194, vcc
	v_sub_f32_e32 v198, v198, v200
	v_add_f32_e32 v200, v199, v198
	v_lshlrev_b64 v[198:199], 6, v[186:187]
	v_lshl_add_u64 v[198:199], v[176:177], 0, v[198:199]
	v_add_co_u32_e32 v198, vcc, 0xffffffa0, v198
	s_nop 1
	v_addc_co_u32_e32 v199, vcc, -1, v199, vcc
	flat_store_dword v[198:199], v200
	s_andn2_saveexec_b64 s[24:25], s[92:93]
	s_cbranch_execnz .LBB0_1047

; DI float softplus_fast(float x) { return fmaxf(x, 0.f) + __logf(1.f + __expf(-fabsf(x))); }
.LBB0_1033:
	v_lshl_add_u64 v[198:199], v[152:153], 2, s[28:29]
	v_mov_b32_e32 v198, v229
	v_add_f32_e32 v198, v53, v198
	v_max_f32_e32 v199, 0, v198
	v_mul_f32_e64 v198, |v198|, s46
	v_exp_f32_e32 v198, v198
	s_nop 0
	v_add_f32_e32 v198, 1.0, v198
	v_cmp_gt_f32_e32 vcc, s47, v198
	s_nop 1
	v_cndmask_b32_e64 v200, 0, 32, vcc
	v_ldexp_f32 v198, v198, v200
	v_log_f32_e32 v198, v198
	s_nop 0
	v_mul_f32_e32 v200, 0x3f317217, v198
	v_fma_f32 v200, v198, s94, -v200
	v_fmac_f32_e32 v200, 0x3377d1cf, v198
	v_fmac_f32_e32 v200, 0x3f317217, v198
	v_cmp_lt_f32_e64 s[24:25], |v198|, s51
	s_nop 1
	v_cndmask_b32_e64 v198, v198, v200, s[24:25]
	v_cndmask_b32_e32 v200, 0, v194, vcc
	v_sub_f32_e32 v198, v198, v200
	v_add_f32_e32 v200, v199, v198
	v_lshlrev_b64 v[198:199], 6, v[186:187]
	v_lshl_add_u64 v[198:199], s[42:43], 0, v[198:199]
	v_lshl_add_u64 v[198:199], v[174:175], 2, v[198:199]
	v_add_co_u32_e32 v198, vcc, 0xffffffa0, v198
	s_nop 1
	v_addc_co_u32_e32 v199, vcc, -1, v199, vcc
	flat_store_dword v[198:199], v200
	s_andn2_saveexec_b64 s[24:25], s[92:93]
	s_cbranch_execnz .LBB0_1049

; DI float softplus_fast(float x) { return fmaxf(x, 0.f) + __logf(1.f + __expf(-fabsf(x))); }
.LBB0_1035:
	v_lshl_add_u64 v[198:199], v[152:153], 2, s[28:29]
	v_mov_b32_e32 v198, v230
	v_add_f32_e32 v198, v54, v198
	v_max_f32_e32 v199, 0, v198
	v_mul_f32_e64 v198, |v198|, s46
	v_exp_f32_e32 v198, v198
	s_nop 0
	v_add_f32_e32 v198, 1.0, v198
	v_cmp_gt_f32_e32 vcc, s47, v198
	s_nop 1
	v_cndmask_b32_e64 v200, 0, 32, vcc
	v_ldexp_f32 v198, v198, v200
	v_log_f32_e32 v198, v198
	s_nop 0
	v_mul_f32_e32 v200, 0x3f317217, v198
	v_fma_f32 v200, v198, s94, -v200
	v_fmac_f32_e32 v200, 0x3377d1cf, v198
	v_fmac_f32_e32 v200, 0x3f317217, v198
	v_cmp_lt_f32_e64 s[24:25], |v198|, s51
	s_nop 1
	v_cndmask_b32_e64 v198, v198, v200, s[24:25]
	v_cndmask_b32_e32 v200, 0, v194, vcc
	v_sub_f32_e32 v198, v198, v200
	v_add_f32_e32 v200, v199, v198
	v_lshlrev_b64 v[198:199], 6, v[186:187]
	v_lshl_add_u64 v[198:199], s[42:43], 0, v[198:199]
	v_lshl_add_u64 v[198:199], v[170:171], 2, v[198:199]
	v_add_co_u32_e32 v198, vcc, 0xffffffa0, v198
	s_nop 1
	v_addc_co_u32_e32 v199, vcc, -1, v199, vcc
	flat_store_dword v[198:199], v200
	s_andn2_saveexec_b64 s[24:25], s[92:93]
	s_cbranch_execnz .LBB0_1051

; DI float softplus_fast(float x) { return fmaxf(x, 0.f) + __logf(1.f + __expf(-fabsf(x))); }
.LBB0_1037:
	v_lshl_add_u64 v[198:199], v[152:153], 2, s[28:29]
	v_mov_b32_e32 v198, v231
	v_add_f32_e32 v198, v55, v198
	v_max_f32_e32 v199, 0, v198
	v_mul_f32_e64 v198, |v198|, s46
	v_exp_f32_e32 v198, v198
	s_nop 0
	v_add_f32_e32 v198, 1.0, v198
	v_cmp_gt_f32_e32 vcc, s47, v198
	s_nop 1
	v_cndmask_b32_e64 v200, 0, 32, vcc
	v_ldexp_f32 v198, v198, v200
	v_log_f32_e32 v198, v198
	s_nop 0
	v_mul_f32_e32 v200, 0x3f317217, v198
	v_fma_f32 v200, v198, s94, -v200
	v_fmac_f32_e32 v200, 0x3377d1cf, v198
	v_fmac_f32_e32 v200, 0x3f317217, v198
	v_cmp_lt_f32_e64 s[24:25], |v198|, s51
	s_nop 1
	v_cndmask_b32_e64 v198, v198, v200, s[24:25]
	v_cndmask_b32_e32 v200, 0, v194, vcc
	v_sub_f32_e32 v198, v198, v200
	v_add_f32_e32 v200, v199, v198
	v_lshlrev_b64 v[198:199], 6, v[186:187]
	v_lshl_add_u64 v[198:199], s[42:43], 0, v[198:199]
	v_lshl_add_u64 v[198:199], v[166:167], 2, v[198:199]
	v_add_co_u32_e32 v198, vcc, 0xffffffa0, v198
	s_nop 1
	v_addc_co_u32_e32 v199, vcc, -1, v199, vcc
	flat_store_dword v[198:199], v200
	s_andn2_saveexec_b64 s[24:25], s[92:93]
	s_cbranch_execnz .LBB0_1053

; DI float softplus_fast(float x) { return fmaxf(x, 0.f) + __logf(1.f + __expf(-fabsf(x))); }
.LBB0_1039:
	v_lshl_add_u64 v[198:199], v[152:153], 2, s[28:29]
	v_mov_b32_e32 v198, v232
	v_add_f32_e32 v198, v48, v198
	v_max_f32_e32 v199, 0, v198
	v_mul_f32_e64 v198, |v198|, s46
	v_exp_f32_e32 v198, v198
	s_nop 0
	v_add_f32_e32 v198, 1.0, v198
	v_cmp_gt_f32_e32 vcc, s47, v198
	s_nop 1
	v_cndmask_b32_e64 v200, 0, 32, vcc
	v_ldexp_f32 v198, v198, v200
	v_log_f32_e32 v198, v198
	s_nop 0
	v_mul_f32_e32 v200, 0x3f317217, v198
	v_fma_f32 v200, v198, s94, -v200
	v_fmac_f32_e32 v200, 0x3377d1cf, v198
	v_fmac_f32_e32 v200, 0x3f317217, v198
	v_cmp_lt_f32_e64 s[24:25], |v198|, s51
	s_nop 1
	v_cndmask_b32_e64 v198, v198, v200, s[24:25]
	v_cndmask_b32_e32 v200, 0, v194, vcc
	v_sub_f32_e32 v198, v198, v200
	v_add_f32_e32 v200, v199, v198
	v_lshlrev_b64 v[198:199], 6, v[186:187]
	v_lshl_add_u64 v[198:199], s[42:43], 0, v[198:199]
	v_lshl_add_u64 v[198:199], v[162:163], 2, v[198:199]
	v_add_co_u32_e32 v198, vcc, 0xffffffa0, v198
	s_nop 1
	v_addc_co_u32_e32 v199, vcc, -1, v199, vcc
	flat_store_dword v[198:199], v200
	s_andn2_saveexec_b64 s[24:25], s[92:93]
	s_cbranch_execnz .LBB0_1055

; DI float softplus_fast(float x) { return fmaxf(x, 0.f) + __logf(1.f + __expf(-fabsf(x))); }
.LBB0_1041:
	v_lshl_add_u64 v[198:199], v[152:153], 2, s[28:29]
	v_mov_b32_e32 v198, v233
	v_add_f32_e32 v198, v49, v198
	v_max_f32_e32 v199, 0, v198
	v_mul_f32_e64 v198, |v198|, s46
	v_exp_f32_e32 v198, v198
	s_nop 0
	v_add_f32_e32 v198, 1.0, v198
	v_cmp_gt_f32_e32 vcc, s47, v198
	s_nop 1
	v_cndmask_b32_e64 v200, 0, 32, vcc
	v_ldexp_f32 v198, v198, v200
	v_log_f32_e32 v198, v198
	s_nop 0
	v_mul_f32_e32 v200, 0x3f317217, v198
	v_fma_f32 v200, v198, s94, -v200
	v_fmac_f32_e32 v200, 0x3377d1cf, v198
	v_fmac_f32_e32 v200, 0x3f317217, v198
	v_cmp_lt_f32_e64 s[24:25], |v198|, s51
	s_nop 1
	v_cndmask_b32_e64 v198, v198, v200, s[24:25]
	v_cndmask_b32_e32 v200, 0, v194, vcc
	v_sub_f32_e32 v198, v198, v200
	v_add_f32_e32 v200, v199, v198
	v_lshlrev_b64 v[198:199], 6, v[186:187]
	v_lshl_add_u64 v[198:199], s[42:43], 0, v[198:199]
	v_lshl_add_u64 v[198:199], v[140:141], 2, v[198:199]
	v_add_co_u32_e32 v198, vcc, 0xffffffa0, v198
	s_nop 1
	v_addc_co_u32_e32 v199, vcc, -1, v199, vcc
	flat_store_dword v[198:199], v200
	s_andn2_saveexec_b64 s[24:25], s[92:93]
	s_cbranch_execnz .LBB0_1057

; DI float softplus_fast(float x) { return fmaxf(x, 0.f) + __logf(1.f + __expf(-fabsf(x))); }
.LBB0_1043:
	v_lshl_add_u64 v[198:199], v[152:153], 2, s[28:29]
	v_mov_b32_e32 v198, v234
	v_add_f32_e32 v198, v50, v198
	v_max_f32_e32 v199, 0, v198
	v_mul_f32_e64 v198, |v198|, s46
	v_exp_f32_e32 v198, v198
	s_nop 0
	v_add_f32_e32 v198, 1.0, v198
	v_cmp_gt_f32_e32 vcc, s47, v198
	s_nop 1
	v_cndmask_b32_e64 v200, 0, 32, vcc
	v_ldexp_f32 v198, v198, v200
	v_log_f32_e32 v198, v198
	s_nop 0
	v_mul_f32_e32 v200, 0x3f317217, v198
	v_fma_f32 v200, v198, s94, -v200
	v_fmac_f32_e32 v200, 0x3377d1cf, v198
	v_fmac_f32_e32 v200, 0x3f317217, v198
	v_cmp_lt_f32_e64 s[24:25], |v198|, s51
	s_nop 1
	v_cndmask_b32_e64 v198, v198, v200, s[24:25]
	v_cndmask_b32_e32 v200, 0, v194, vcc
	v_sub_f32_e32 v198, v198, v200
	v_add_f32_e32 v200, v199, v198
	v_lshlrev_b64 v[198:199], 6, v[186:187]
	v_lshl_add_u64 v[198:199], s[42:43], 0, v[198:199]
	v_lshl_add_u64 v[198:199], v[136:137], 2, v[198:199]
	v_add_co_u32_e32 v198, vcc, 0xffffffa0, v198
	s_nop 1
	v_addc_co_u32_e32 v199, vcc, -1, v199, vcc
	flat_store_dword v[198:199], v200
	s_andn2_saveexec_b64 s[24:25], s[92:93]
	s_cbranch_execnz .LBB0_1059

; DI float softplus_fast(float x) { return fmaxf(x, 0.f) + __logf(1.f + __expf(-fabsf(x))); }
.LBB0_1045:
	v_lshl_add_u64 v[198:199], v[152:153], 2, s[28:29]
	v_mov_b32_e32 v198, v235
	v_lshlrev_b64 v[186:187], 6, v[186:187]
	v_lshl_add_u64 v[186:187], s[42:43], 0, v[186:187]
	v_lshl_add_u64 v[186:187], v[132:133], 2, v[186:187]
	v_add_f32_e32 v198, v51, v198
	v_max_f32_e32 v199, 0, v198
	v_mul_f32_e64 v198, |v198|, s46
	v_exp_f32_e32 v198, v198
	s_nop 0
	v_add_f32_e32 v198, 1.0, v198
	v_cmp_gt_f32_e32 vcc, s47, v198
	s_nop 1
	v_cndmask_b32_e64 v200, 0, 32, vcc
	v_ldexp_f32 v198, v198, v200
	v_log_f32_e32 v198, v198
	s_nop 0
	v_mul_f32_e32 v200, 0x3f317217, v198
	v_fma_f32 v200, v198, s94, -v200
	v_fmac_f32_e32 v200, 0x3377d1cf, v198
	v_fmac_f32_e32 v200, 0x3f317217, v198
	v_cmp_lt_f32_e64 s[24:25], |v198|, s51
	s_nop 1
	v_cndmask_b32_e64 v198, v198, v200, s[24:25]
	v_cndmask_b32_e32 v200, 0, v194, vcc
	v_sub_f32_e32 v198, v198, v200
	v_add_co_u32_e32 v186, vcc, 0xffffffa0, v186
	v_add_f32_e32 v198, v199, v198
	s_nop 0
	v_addc_co_u32_e32 v187, vcc, -1, v187, vcc
	flat_store_dword v[186:187], v198
	s_andn2_saveexec_b64 s[24:25], s[92:93]
	s_cbranch_execnz .LBB0_1061
	s_branch .LBB0_1062

; #define TS_(e) { const unsigned w0_ = pk2(ta0[e], ta1[e]); vt[(size_t)(e) * SEQ] = (bf16_t)(w0_ & 0xffff); vt[(size_t)((e) + 4) * SEQ] = (bf16_t)(w0_ >> 16); }
; #define GV_(n, e) { const int c_ = cb + 4 * (n) + (e); const float v_ = (n) ? tb1[e] : tb0[e]; if (c_ < 24) GATES[(size_t)row * 24 + c_] = sigmoidf_(v_); else if (c_ < 40) DT[(size_t)row * 16 + c_ - 24] = softplus_fast(v_ + dt_bias[c_ - 24]); }
;     DI void operator()(const Acc& acc, const Unit& u, int wr, int wc, int fr, int fq) const {
;     ...
;                 else { bf16_t* vt = VWT + ((size_t)(b * 2 + h) * 64 + d0) * SEQ + t; const f32x4 ta0 = acc[ai][0][m][0], ta1 = acc[ai][0][m][1]; TS_(0) TS_(1) TS_(2) TS_(3)
;                   const int cb = wc * 32 + 8 * fq; const f32x4 tb0 = acc[ai][1][m][0], tb1 = acc[ai][1][m][1];
;                   if (cb < 40) { GV_(0, 0) GV_(0, 1) GV_(0, 2) GV_(0, 3) GV_(1, 0) GV_(1, 1) GV_(1, 2) GV_(1, 3) } } )
.LBB0_1065:
	v_add_u32_e32 v186, 0x90, v182
	v_and_b32_e32 v183, 0x1fff, v186
	v_ashrrev_i32_e32 v197, 13, v186
	s_and_b64 vcc, exec, s[22:23]
	s_mov_b64 s[24:25], -1
	s_cbranch_vccnz .LBB0_1100
	v_lshl_or_b32 v198, v197, 1, s63
	v_ashrrev_i32_e32 v199, 31, v198
	v_lshlrev_b64 v[198:199], 20, v[198:199]
	v_lshl_add_u64 v[198:199], v[180:181], 0, v[198:199]
	v_lshlrev_b32_e32 v200, 1, v183
	v_mov_b32_e32 v201, v153
	v_lshl_add_u64 v[198:199], v[198:199], 0, v[200:201]
	v_add_co_u32_e32 v200, vcc, 0x10000, v198
	v_cvt_pk_bf16_f32 v187, v44, v40
	s_nop 0
	v_addc_co_u32_e32 v201, vcc, 0, v199, vcc
	flat_store_short_d16_hi v[200:201], v187
	v_add_co_u32_e32 v200, vcc, 0x4000, v198
	flat_store_short v[198:199], v187
	v_cvt_pk_bf16_f32 v187, v45, v41
	v_addc_co_u32_e32 v201, vcc, 0, v199, vcc
	flat_store_short v[200:201], v187
	v_add_co_u32_e32 v200, vcc, 0x14000, v198
	s_nop 1
	v_addc_co_u32_e32 v201, vcc, 0, v199, vcc
	flat_store_short_d16_hi v[200:201], v187
	v_add_co_u32_e32 v200, vcc, 0x8000, v198
	v_cvt_pk_bf16_f32 v187, v46, v42
	s_nop 0
	v_addc_co_u32_e32 v201, vcc, 0, v199, vcc
	flat_store_short v[200:201], v187
	v_add_co_u32_e32 v200, vcc, 0x18000, v198
	s_nop 1
	v_addc_co_u32_e32 v201, vcc, 0, v199, vcc
	flat_store_short_d16_hi v[200:201], v187
	v_add_co_u32_e32 v200, vcc, 0xc000, v198
	v_cvt_pk_bf16_f32 v187, v47, v43
	s_nop 0
	v_addc_co_u32_e32 v201, vcc, 0, v199, vcc
	v_add_co_u32_e32 v198, vcc, 0x1c000, v198
	flat_store_short v[200:201], v187
	s_nop 0
	v_addc_co_u32_e32 v199, vcc, 0, v199, vcc
	flat_store_short_d16_hi v[198:199], v187
	s_and_saveexec_b64 s[90:91], s[20:21]
	s_cbranch_execz .LBB0_1099
	v_ashrrev_i32_e32 v187, 31, v186
	s_and_saveexec_b64 s[24:25], s[18:19]
	s_xor_b64 s[92:93], exec, s[24:25]
	s_cbranch_execz .LBB0_1083
	v_lshl_add_u64 v[198:199], v[152:153], 2, s[28:29]
	v_mov_b32_e32 v198, v228
	v_add_f32_e32 v198, v36, v198
	v_max_f32_e32 v199, 0, v198
	v_mul_f32_e64 v198, |v198|, s46
	v_exp_f32_e32 v198, v198
	s_nop 0
	v_add_f32_e32 v198, 1.0, v198
	v_cmp_gt_f32_e32 vcc, s47, v198
	s_nop 1
	v_cndmask_b32_e64 v200, 0, 32, vcc
	v_ldexp_f32 v198, v198, v200
	v_log_f32_e32 v198, v198
	s_nop 0
	v_mul_f32_e32 v200, 0x3f317217, v198
	v_fma_f32 v200, v198, s94, -v200
	v_fmac_f32_e32 v200, 0x3377d1cf, v198
	v_fmac_f32_e32 v200, 0x3f317217, v198
	v_cmp_lt_f32_e64 s[24:25], |v198|, s51
	s_nop 1
	v_cndmask_b32_e64 v198, v198, v200, s[24:25]
	v_cndmask_b32_e32 v200, 0, v194, vcc
	v_sub_f32_e32 v198, v198, v200
	v_add_f32_e32 v200, v199, v198
	v_lshlrev_b64 v[198:199], 6, v[186:187]
	v_lshl_add_u64 v[198:199], v[176:177], 0, v[198:199]
	v_add_co_u32_e32 v198, vcc, 0xffffffa0, v198
	s_nop 1
	v_addc_co_u32_e32 v199, vcc, -1, v199, vcc
	flat_store_dword v[198:199], v200
	s_andn2_saveexec_b64 s[24:25], s[92:93]
	s_cbranch_execnz .LBB0_1084

; DI float softplus_fast(float x) { return fmaxf(x, 0.f) + __logf(1.f + __expf(-fabsf(x))); }
.LBB0_1070:
	v_lshl_add_u64 v[198:199], v[152:153], 2, s[28:29]
	v_mov_b32_e32 v198, v229
	v_add_f32_e32 v198, v37, v198
	v_max_f32_e32 v199, 0, v198
	v_mul_f32_e64 v198, |v198|, s46
	v_exp_f32_e32 v198, v198
	s_nop 0
	v_add_f32_e32 v198, 1.0, v198
	v_cmp_gt_f32_e32 vcc, s47, v198
	s_nop 1
	v_cndmask_b32_e64 v200, 0, 32, vcc
	v_ldexp_f32 v198, v198, v200
	v_log_f32_e32 v198, v198
	s_nop 0
	v_mul_f32_e32 v200, 0x3f317217, v198
	v_fma_f32 v200, v198, s94, -v200
	v_fmac_f32_e32 v200, 0x3377d1cf, v198
	v_fmac_f32_e32 v200, 0x3f317217, v198
	v_cmp_lt_f32_e64 s[24:25], |v198|, s51
	s_nop 1
	v_cndmask_b32_e64 v198, v198, v200, s[24:25]
	v_cndmask_b32_e32 v200, 0, v194, vcc
	v_sub_f32_e32 v198, v198, v200
	v_add_f32_e32 v200, v199, v198
	v_lshlrev_b64 v[198:199], 6, v[186:187]
	v_lshl_add_u64 v[198:199], s[42:43], 0, v[198:199]
	v_lshl_add_u64 v[198:199], v[174:175], 2, v[198:199]
	v_add_co_u32_e32 v198, vcc, 0xffffffa0, v198
	s_nop 1
	v_addc_co_u32_e32 v199, vcc, -1, v199, vcc
	flat_store_dword v[198:199], v200
	s_andn2_saveexec_b64 s[24:25], s[92:93]
	s_cbranch_execnz .LBB0_1086

; DI float softplus_fast(float x) { return fmaxf(x, 0.f) + __logf(1.f + __expf(-fabsf(x))); }
.LBB0_1072:
	v_lshl_add_u64 v[198:199], v[152:153], 2, s[28:29]
	v_mov_b32_e32 v198, v230
	v_add_f32_e32 v198, v38, v198
	v_max_f32_e32 v199, 0, v198
	v_mul_f32_e64 v198, |v198|, s46
	v_exp_f32_e32 v198, v198
	s_nop 0
	v_add_f32_e32 v198, 1.0, v198
	v_cmp_gt_f32_e32 vcc, s47, v198
	s_nop 1
	v_cndmask_b32_e64 v200, 0, 32, vcc
	v_ldexp_f32 v198, v198, v200
	v_log_f32_e32 v198, v198
	s_nop 0
	v_mul_f32_e32 v200, 0x3f317217, v198
	v_fma_f32 v200, v198, s94, -v200
	v_fmac_f32_e32 v200, 0x3377d1cf, v198
	v_fmac_f32_e32 v200, 0x3f317217, v198
	v_cmp_lt_f32_e64 s[24:25], |v198|, s51
	s_nop 1
	v_cndmask_b32_e64 v198, v198, v200, s[24:25]
	v_cndmask_b32_e32 v200, 0, v194, vcc
	v_sub_f32_e32 v198, v198, v200
	v_add_f32_e32 v200, v199, v198
	v_lshlrev_b64 v[198:199], 6, v[186:187]
	v_lshl_add_u64 v[198:199], s[42:43], 0, v[198:199]
	v_lshl_add_u64 v[198:199], v[170:171], 2, v[198:199]
	v_add_co_u32_e32 v198, vcc, 0xffffffa0, v198
	s_nop 1
	v_addc_co_u32_e32 v199, vcc, -1, v199, vcc
	flat_store_dword v[198:199], v200
	s_andn2_saveexec_b64 s[24:25], s[92:93]
	s_cbranch_execnz .LBB0_1088

; DI float softplus_fast(float x) { return fmaxf(x, 0.f) + __logf(1.f + __expf(-fabsf(x))); }
.LBB0_1074:
	v_lshl_add_u64 v[198:199], v[152:153], 2, s[28:29]
	v_mov_b32_e32 v198, v231
	v_add_f32_e32 v198, v39, v198
	v_max_f32_e32 v199, 0, v198
	v_mul_f32_e64 v198, |v198|, s46
	v_exp_f32_e32 v198, v198
	s_nop 0
	v_add_f32_e32 v198, 1.0, v198
	v_cmp_gt_f32_e32 vcc, s47, v198
	s_nop 1
	v_cndmask_b32_e64 v200, 0, 32, vcc
	v_ldexp_f32 v198, v198, v200
	v_log_f32_e32 v198, v198
	s_nop 0
	v_mul_f32_e32 v200, 0x3f317217, v198
	v_fma_f32 v200, v198, s94, -v200
	v_fmac_f32_e32 v200, 0x3377d1cf, v198
	v_fmac_f32_e32 v200, 0x3f317217, v198
	v_cmp_lt_f32_e64 s[24:25], |v198|, s51
	s_nop 1
	v_cndmask_b32_e64 v198, v198, v200, s[24:25]
	v_cndmask_b32_e32 v200, 0, v194, vcc
	v_sub_f32_e32 v198, v198, v200
	v_add_f32_e32 v200, v199, v198
	v_lshlrev_b64 v[198:199], 6, v[186:187]
	v_lshl_add_u64 v[198:199], s[42:43], 0, v[198:199]
	v_lshl_add_u64 v[198:199], v[166:167], 2, v[198:199]
	v_add_co_u32_e32 v198, vcc, 0xffffffa0, v198
	s_nop 1
	v_addc_co_u32_e32 v199, vcc, -1, v199, vcc
	flat_store_dword v[198:199], v200
	s_andn2_saveexec_b64 s[24:25], s[92:93]
	s_cbranch_execnz .LBB0_1090

; DI float softplus_fast(float x) { return fmaxf(x, 0.f) + __logf(1.f + __expf(-fabsf(x))); }
.LBB0_1076:
	v_lshl_add_u64 v[198:199], v[152:153], 2, s[28:29]
	v_mov_b32_e32 v198, v232
	v_add_f32_e32 v198, v32, v198
	v_max_f32_e32 v199, 0, v198
	v_mul_f32_e64 v198, |v198|, s46
	v_exp_f32_e32 v198, v198
	s_nop 0
	v_add_f32_e32 v198, 1.0, v198
	v_cmp_gt_f32_e32 vcc, s47, v198
	s_nop 1
	v_cndmask_b32_e64 v200, 0, 32, vcc
	v_ldexp_f32 v198, v198, v200
	v_log_f32_e32 v198, v198
	s_nop 0
	v_mul_f32_e32 v200, 0x3f317217, v198
	v_fma_f32 v200, v198, s94, -v200
	v_fmac_f32_e32 v200, 0x3377d1cf, v198
	v_fmac_f32_e32 v200, 0x3f317217, v198
	v_cmp_lt_f32_e64 s[24:25], |v198|, s51
	s_nop 1
	v_cndmask_b32_e64 v198, v198, v200, s[24:25]
	v_cndmask_b32_e32 v200, 0, v194, vcc
	v_sub_f32_e32 v198, v198, v200
	v_add_f32_e32 v200, v199, v198
	v_lshlrev_b64 v[198:199], 6, v[186:187]
	v_lshl_add_u64 v[198:199], s[42:43], 0, v[198:199]
	v_lshl_add_u64 v[198:199], v[162:163], 2, v[198:199]
	v_add_co_u32_e32 v198, vcc, 0xffffffa0, v198
	s_nop 1
	v_addc_co_u32_e32 v199, vcc, -1, v199, vcc
	flat_store_dword v[198:199], v200
	s_andn2_saveexec_b64 s[24:25], s[92:93]
	s_cbranch_execnz .LBB0_1092

; DI float softplus_fast(float x) { return fmaxf(x, 0.f) + __logf(1.f + __expf(-fabsf(x))); }
.LBB0_1078:
	v_lshl_add_u64 v[198:199], v[152:153], 2, s[28:29]
	v_mov_b32_e32 v198, v233
	v_add_f32_e32 v198, v33, v198
	v_max_f32_e32 v199, 0, v198
	v_mul_f32_e64 v198, |v198|, s46
	v_exp_f32_e32 v198, v198
	s_nop 0
	v_add_f32_e32 v198, 1.0, v198
	v_cmp_gt_f32_e32 vcc, s47, v198
	s_nop 1
	v_cndmask_b32_e64 v200, 0, 32, vcc
	v_ldexp_f32 v198, v198, v200
	v_log_f32_e32 v198, v198
	s_nop 0
	v_mul_f32_e32 v200, 0x3f317217, v198
	v_fma_f32 v200, v198, s94, -v200
	v_fmac_f32_e32 v200, 0x3377d1cf, v198
	v_fmac_f32_e32 v200, 0x3f317217, v198
	v_cmp_lt_f32_e64 s[24:25], |v198|, s51
	s_nop 1
	v_cndmask_b32_e64 v198, v198, v200, s[24:25]
	v_cndmask_b32_e32 v200, 0, v194, vcc
	v_sub_f32_e32 v198, v198, v200
	v_add_f32_e32 v200, v199, v198
	v_lshlrev_b64 v[198:199], 6, v[186:187]
	v_lshl_add_u64 v[198:199], s[42:43], 0, v[198:199]
	v_lshl_add_u64 v[198:199], v[140:141], 2, v[198:199]
	v_add_co_u32_e32 v198, vcc, 0xffffffa0, v198
	s_nop 1
	v_addc_co_u32_e32 v199, vcc, -1, v199, vcc
	flat_store_dword v[198:199], v200
	s_andn2_saveexec_b64 s[24:25], s[92:93]
	s_cbranch_execnz .LBB0_1094

; DI float softplus_fast(float x) { return fmaxf(x, 0.f) + __logf(1.f + __expf(-fabsf(x))); }
.LBB0_1080:
	v_lshl_add_u64 v[198:199], v[152:153], 2, s[28:29]
	v_mov_b32_e32 v198, v234
	v_add_f32_e32 v198, v34, v198
	v_max_f32_e32 v199, 0, v198
	v_mul_f32_e64 v198, |v198|, s46
	v_exp_f32_e32 v198, v198
	s_nop 0
	v_add_f32_e32 v198, 1.0, v198
	v_cmp_gt_f32_e32 vcc, s47, v198
	s_nop 1
	v_cndmask_b32_e64 v200, 0, 32, vcc
	v_ldexp_f32 v198, v198, v200
	v_log_f32_e32 v198, v198
	s_nop 0
	v_mul_f32_e32 v200, 0x3f317217, v198
	v_fma_f32 v200, v198, s94, -v200
	v_fmac_f32_e32 v200, 0x3377d1cf, v198
	v_fmac_f32_e32 v200, 0x3f317217, v198
	v_cmp_lt_f32_e64 s[24:25], |v198|, s51
	s_nop 1
	v_cndmask_b32_e64 v198, v198, v200, s[24:25]
	v_cndmask_b32_e32 v200, 0, v194, vcc
	v_sub_f32_e32 v198, v198, v200
	v_add_f32_e32 v200, v199, v198
	v_lshlrev_b64 v[198:199], 6, v[186:187]
	v_lshl_add_u64 v[198:199], s[42:43], 0, v[198:199]
	v_lshl_add_u64 v[198:199], v[136:137], 2, v[198:199]
	v_add_co_u32_e32 v198, vcc, 0xffffffa0, v198
	s_nop 1
	v_addc_co_u32_e32 v199, vcc, -1, v199, vcc
	flat_store_dword v[198:199], v200
	s_andn2_saveexec_b64 s[24:25], s[92:93]
	s_cbranch_execnz .LBB0_1096

; DI float softplus_fast(float x) { return fmaxf(x, 0.f) + __logf(1.f + __expf(-fabsf(x))); }
.LBB0_1082:
	v_lshl_add_u64 v[198:199], v[152:153], 2, s[28:29]
	v_mov_b32_e32 v198, v235
	v_lshlrev_b64 v[186:187], 6, v[186:187]
	v_lshl_add_u64 v[186:187], s[42:43], 0, v[186:187]
	v_lshl_add_u64 v[186:187], v[132:133], 2, v[186:187]
	v_add_f32_e32 v198, v35, v198
	v_max_f32_e32 v199, 0, v198
	v_mul_f32_e64 v198, |v198|, s46
	v_exp_f32_e32 v198, v198
	s_nop 0
	v_add_f32_e32 v198, 1.0, v198
	v_cmp_gt_f32_e32 vcc, s47, v198
	s_nop 1
	v_cndmask_b32_e64 v200, 0, 32, vcc
	v_ldexp_f32 v198, v198, v200
	v_log_f32_e32 v198, v198
	s_nop 0
	v_mul_f32_e32 v200, 0x3f317217, v198
	v_fma_f32 v200, v198, s94, -v200
	v_fmac_f32_e32 v200, 0x3377d1cf, v198
	v_fmac_f32_e32 v200, 0x3f317217, v198
	v_cmp_lt_f32_e64 s[24:25], |v198|, s51
	s_nop 1
	v_cndmask_b32_e64 v198, v198, v200, s[24:25]
	v_cndmask_b32_e32 v200, 0, v194, vcc
	v_sub_f32_e32 v198, v198, v200
	v_add_co_u32_e32 v186, vcc, 0xffffffa0, v186
	v_add_f32_e32 v198, v199, v198
	s_nop 0
	v_addc_co_u32_e32 v187, vcc, -1, v187, vcc
	flat_store_dword v[186:187], v198
	s_andn2_saveexec_b64 s[24:25], s[92:93]
	s_cbranch_execnz .LBB0_1098
	s_branch .LBB0_1099

; #define TS_(e) { const unsigned w0_ = pk2(ta0[e], ta1[e]); vt[(size_t)(e) * SEQ] = (bf16_t)(w0_ & 0xffff); vt[(size_t)((e) + 4) * SEQ] = (bf16_t)(w0_ >> 16); }
; #define GV_(n, e) { const int c_ = cb + 4 * (n) + (e); const float v_ = (n) ? tb1[e] : tb0[e]; if (c_ < 24) GATES[(size_t)row * 24 + c_] = sigmoidf_(v_); else if (c_ < 40) DT[(size_t)row * 16 + c_ - 24] = softplus_fast(v_ + dt_bias[c_ - 24]); }
;     DI void operator()(const Acc& acc, const Unit& u, int wr, int wc, int fr, int fq) const {
;     ...
;                 else { bf16_t* vt = VWT + ((size_t)(b * 2 + h) * 64 + d0) * SEQ + t; const f32x4 ta0 = acc[ai][0][m][0], ta1 = acc[ai][0][m][1]; TS_(0) TS_(1) TS_(2) TS_(3)
;                   const int cb = wc * 32 + 8 * fq; const f32x4 tb0 = acc[ai][1][m][0], tb1 = acc[ai][1][m][1];
;                   if (cb < 40) { GV_(0, 0) GV_(0, 1) GV_(0, 2) GV_(0, 3) GV_(1, 0) GV_(1, 1) GV_(1, 2) GV_(1, 3) } } )
.LBB0_1102:
	v_add_u32_e32 v186, 0xa0, v182
	v_and_b32_e32 v183, 0x1fff, v186
	v_ashrrev_i32_e32 v197, 13, v186
	s_and_b64 vcc, exec, s[22:23]
	s_mov_b64 s[24:25], -1
	s_cbranch_vccnz .LBB0_1137
	v_lshl_or_b32 v198, v197, 1, s63
	v_ashrrev_i32_e32 v199, 31, v198
	v_lshlrev_b64 v[198:199], 20, v[198:199]
	v_lshl_add_u64 v[198:199], v[180:181], 0, v[198:199]
	v_lshlrev_b32_e32 v200, 1, v183
	v_mov_b32_e32 v201, v153
	v_lshl_add_u64 v[198:199], v[198:199], 0, v[200:201]
	v_add_co_u32_e32 v200, vcc, 0x10000, v198
	v_cvt_pk_bf16_f32 v187, v28, v24
	s_nop 0
	v_addc_co_u32_e32 v201, vcc, 0, v199, vcc
	flat_store_short_d16_hi v[200:201], v187
	v_add_co_u32_e32 v200, vcc, 0x4000, v198
	flat_store_short v[198:199], v187
	v_cvt_pk_bf16_f32 v187, v29, v25
	v_addc_co_u32_e32 v201, vcc, 0, v199, vcc
	flat_store_short v[200:201], v187
	v_add_co_u32_e32 v200, vcc, 0x14000, v198
	s_nop 1
	v_addc_co_u32_e32 v201, vcc, 0, v199, vcc
	flat_store_short_d16_hi v[200:201], v187
	v_add_co_u32_e32 v200, vcc, 0x8000, v198
	v_cvt_pk_bf16_f32 v187, v30, v26
	s_nop 0
	v_addc_co_u32_e32 v201, vcc, 0, v199, vcc
	flat_store_short v[200:201], v187
	v_add_co_u32_e32 v200, vcc, 0x18000, v198
	s_nop 1
	v_addc_co_u32_e32 v201, vcc, 0, v199, vcc
	flat_store_short_d16_hi v[200:201], v187
	v_add_co_u32_e32 v200, vcc, 0xc000, v198
	v_cvt_pk_bf16_f32 v187, v31, v27
	s_nop 0
	v_addc_co_u32_e32 v201, vcc, 0, v199, vcc
	v_add_co_u32_e32 v198, vcc, 0x1c000, v198
	flat_store_short v[200:201], v187
	s_nop 0
	v_addc_co_u32_e32 v199, vcc, 0, v199, vcc
	flat_store_short_d16_hi v[198:199], v187
	s_and_saveexec_b64 s[90:91], s[20:21]
	s_cbranch_execz .LBB0_1136
	v_ashrrev_i32_e32 v187, 31, v186
	s_and_saveexec_b64 s[24:25], s[18:19]
	s_xor_b64 s[92:93], exec, s[24:25]
	s_cbranch_execz .LBB0_1120
	v_lshl_add_u64 v[198:199], v[152:153], 2, s[28:29]
	v_mov_b32_e32 v198, v228
	v_add_f32_e32 v198, v20, v198
	v_max_f32_e32 v199, 0, v198
	v_mul_f32_e64 v198, |v198|, s46
	v_exp_f32_e32 v198, v198
	s_nop 0
	v_add_f32_e32 v198, 1.0, v198
	v_cmp_gt_f32_e32 vcc, s47, v198
	s_nop 1
	v_cndmask_b32_e64 v200, 0, 32, vcc
	v_ldexp_f32 v198, v198, v200
	v_log_f32_e32 v198, v198
	s_nop 0
	v_mul_f32_e32 v200, 0x3f317217, v198
	v_fma_f32 v200, v198, s94, -v200
	v_fmac_f32_e32 v200, 0x3377d1cf, v198
	v_fmac_f32_e32 v200, 0x3f317217, v198
	v_cmp_lt_f32_e64 s[24:25], |v198|, s51
	s_nop 1
	v_cndmask_b32_e64 v198, v198, v200, s[24:25]
	v_cndmask_b32_e32 v200, 0, v194, vcc
	v_sub_f32_e32 v198, v198, v200
	v_add_f32_e32 v200, v199, v198
	v_lshlrev_b64 v[198:199], 6, v[186:187]
	v_lshl_add_u64 v[198:199], v[176:177], 0, v[198:199]
	v_add_co_u32_e32 v198, vcc, 0xffffffa0, v198
	s_nop 1
	v_addc_co_u32_e32 v199, vcc, -1, v199, vcc
	flat_store_dword v[198:199], v200
	s_andn2_saveexec_b64 s[24:25], s[92:93]
	s_cbranch_execnz .LBB0_1121

; DI float softplus_fast(float x) { return fmaxf(x, 0.f) + __logf(1.f + __expf(-fabsf(x))); }
.LBB0_1107:
	v_lshl_add_u64 v[198:199], v[152:153], 2, s[28:29]
	v_mov_b32_e32 v198, v229
	v_add_f32_e32 v198, v21, v198
	v_max_f32_e32 v199, 0, v198
	v_mul_f32_e64 v198, |v198|, s46
	v_exp_f32_e32 v198, v198
	s_nop 0
	v_add_f32_e32 v198, 1.0, v198
	v_cmp_gt_f32_e32 vcc, s47, v198
	s_nop 1
	v_cndmask_b32_e64 v200, 0, 32, vcc
	v_ldexp_f32 v198, v198, v200
	v_log_f32_e32 v198, v198
	s_nop 0
	v_mul_f32_e32 v200, 0x3f317217, v198
	v_fma_f32 v200, v198, s94, -v200
	v_fmac_f32_e32 v200, 0x3377d1cf, v198
	v_fmac_f32_e32 v200, 0x3f317217, v198
	v_cmp_lt_f32_e64 s[24:25], |v198|, s51
	s_nop 1
	v_cndmask_b32_e64 v198, v198, v200, s[24:25]
	v_cndmask_b32_e32 v200, 0, v194, vcc
	v_sub_f32_e32 v198, v198, v200
	v_add_f32_e32 v200, v199, v198
	v_lshlrev_b64 v[198:199], 6, v[186:187]
	v_lshl_add_u64 v[198:199], s[42:43], 0, v[198:199]
	v_lshl_add_u64 v[198:199], v[174:175], 2, v[198:199]
	v_add_co_u32_e32 v198, vcc, 0xffffffa0, v198
	s_nop 1
	v_addc_co_u32_e32 v199, vcc, -1, v199, vcc
	flat_store_dword v[198:199], v200
	s_andn2_saveexec_b64 s[24:25], s[92:93]
	s_cbranch_execnz .LBB0_1123

; DI float softplus_fast(float x) { return fmaxf(x, 0.f) + __logf(1.f + __expf(-fabsf(x))); }
.LBB0_1109:
	v_lshl_add_u64 v[198:199], v[152:153], 2, s[28:29]
	v_mov_b32_e32 v198, v230
	v_add_f32_e32 v198, v22, v198
	v_max_f32_e32 v199, 0, v198
	v_mul_f32_e64 v198, |v198|, s46
	v_exp_f32_e32 v198, v198
	s_nop 0
	v_add_f32_e32 v198, 1.0, v198
	v_cmp_gt_f32_e32 vcc, s47, v198
	s_nop 1
	v_cndmask_b32_e64 v200, 0, 32, vcc
	v_ldexp_f32 v198, v198, v200
	v_log_f32_e32 v198, v198
	s_nop 0
	v_mul_f32_e32 v200, 0x3f317217, v198
	v_fma_f32 v200, v198, s94, -v200
	v_fmac_f32_e32 v200, 0x3377d1cf, v198
	v_fmac_f32_e32 v200, 0x3f317217, v198
	v_cmp_lt_f32_e64 s[24:25], |v198|, s51
	s_nop 1
	v_cndmask_b32_e64 v198, v198, v200, s[24:25]
	v_cndmask_b32_e32 v200, 0, v194, vcc
	v_sub_f32_e32 v198, v198, v200
	v_add_f32_e32 v200, v199, v198
	v_lshlrev_b64 v[198:199], 6, v[186:187]
	v_lshl_add_u64 v[198:199], s[42:43], 0, v[198:199]
	v_lshl_add_u64 v[198:199], v[170:171], 2, v[198:199]
	v_add_co_u32_e32 v198, vcc, 0xffffffa0, v198
	s_nop 1
	v_addc_co_u32_e32 v199, vcc, -1, v199, vcc
	flat_store_dword v[198:199], v200
	s_andn2_saveexec_b64 s[24:25], s[92:93]
	s_cbranch_execnz .LBB0_1125

; DI float softplus_fast(float x) { return fmaxf(x, 0.f) + __logf(1.f + __expf(-fabsf(x))); }
.LBB0_1111:
	v_lshl_add_u64 v[198:199], v[152:153], 2, s[28:29]
	v_mov_b32_e32 v198, v231
	v_add_f32_e32 v198, v23, v198
	v_max_f32_e32 v199, 0, v198
	v_mul_f32_e64 v198, |v198|, s46
	v_exp_f32_e32 v198, v198
	s_nop 0
	v_add_f32_e32 v198, 1.0, v198
	v_cmp_gt_f32_e32 vcc, s47, v198
	s_nop 1
	v_cndmask_b32_e64 v200, 0, 32, vcc
	v_ldexp_f32 v198, v198, v200
	v_log_f32_e32 v198, v198
	s_nop 0
	v_mul_f32_e32 v200, 0x3f317217, v198
	v_fma_f32 v200, v198, s94, -v200
	v_fmac_f32_e32 v200, 0x3377d1cf, v198
	v_fmac_f32_e32 v200, 0x3f317217, v198
	v_cmp_lt_f32_e64 s[24:25], |v198|, s51
	s_nop 1
	v_cndmask_b32_e64 v198, v198, v200, s[24:25]
	v_cndmask_b32_e32 v200, 0, v194, vcc
	v_sub_f32_e32 v198, v198, v200
	v_add_f32_e32 v200, v199, v198
	v_lshlrev_b64 v[198:199], 6, v[186:187]
	v_lshl_add_u64 v[198:199], s[42:43], 0, v[198:199]
	v_lshl_add_u64 v[198:199], v[166:167], 2, v[198:199]
	v_add_co_u32_e32 v198, vcc, 0xffffffa0, v198
	s_nop 1
	v_addc_co_u32_e32 v199, vcc, -1, v199, vcc
	flat_store_dword v[198:199], v200
	s_andn2_saveexec_b64 s[24:25], s[92:93]
	s_cbranch_execnz .LBB0_1127

; DI float softplus_fast(float x) { return fmaxf(x, 0.f) + __logf(1.f + __expf(-fabsf(x))); }
.LBB0_1113:
	v_lshl_add_u64 v[198:199], v[152:153], 2, s[28:29]
	v_mov_b32_e32 v198, v232
	v_add_f32_e32 v198, v16, v198
	v_max_f32_e32 v199, 0, v198
	v_mul_f32_e64 v198, |v198|, s46
	v_exp_f32_e32 v198, v198
	s_nop 0
	v_add_f32_e32 v198, 1.0, v198
	v_cmp_gt_f32_e32 vcc, s47, v198
	s_nop 1
	v_cndmask_b32_e64 v200, 0, 32, vcc
	v_ldexp_f32 v198, v198, v200
	v_log_f32_e32 v198, v198
	s_nop 0
	v_mul_f32_e32 v200, 0x3f317217, v198
	v_fma_f32 v200, v198, s94, -v200
	v_fmac_f32_e32 v200, 0x3377d1cf, v198
	v_fmac_f32_e32 v200, 0x3f317217, v198
	v_cmp_lt_f32_e64 s[24:25], |v198|, s51
	s_nop 1
	v_cndmask_b32_e64 v198, v198, v200, s[24:25]
	v_cndmask_b32_e32 v200, 0, v194, vcc
	v_sub_f32_e32 v198, v198, v200
	v_add_f32_e32 v200, v199, v198
	v_lshlrev_b64 v[198:199], 6, v[186:187]
	v_lshl_add_u64 v[198:199], s[42:43], 0, v[198:199]
	v_lshl_add_u64 v[198:199], v[162:163], 2, v[198:199]
	v_add_co_u32_e32 v198, vcc, 0xffffffa0, v198
	s_nop 1
	v_addc_co_u32_e32 v199, vcc, -1, v199, vcc
	flat_store_dword v[198:199], v200
	s_andn2_saveexec_b64 s[24:25], s[92:93]
	s_cbranch_execnz .LBB0_1129

; DI float softplus_fast(float x) { return fmaxf(x, 0.f) + __logf(1.f + __expf(-fabsf(x))); }
.LBB0_1115:
	v_lshl_add_u64 v[198:199], v[152:153], 2, s[28:29]
	v_mov_b32_e32 v198, v233
	v_add_f32_e32 v198, v17, v198
	v_max_f32_e32 v199, 0, v198
	v_mul_f32_e64 v198, |v198|, s46
	v_exp_f32_e32 v198, v198
	s_nop 0
	v_add_f32_e32 v198, 1.0, v198
	v_cmp_gt_f32_e32 vcc, s47, v198
	s_nop 1
	v_cndmask_b32_e64 v200, 0, 32, vcc
	v_ldexp_f32 v198, v198, v200
	v_log_f32_e32 v198, v198
	s_nop 0
	v_mul_f32_e32 v200, 0x3f317217, v198
	v_fma_f32 v200, v198, s94, -v200
	v_fmac_f32_e32 v200, 0x3377d1cf, v198
	v_fmac_f32_e32 v200, 0x3f317217, v198
	v_cmp_lt_f32_e64 s[24:25], |v198|, s51
	s_nop 1
	v_cndmask_b32_e64 v198, v198, v200, s[24:25]
	v_cndmask_b32_e32 v200, 0, v194, vcc
	v_sub_f32_e32 v198, v198, v200
	v_add_f32_e32 v200, v199, v198
	v_lshlrev_b64 v[198:199], 6, v[186:187]
	v_lshl_add_u64 v[198:199], s[42:43], 0, v[198:199]
	v_lshl_add_u64 v[198:199], v[140:141], 2, v[198:199]
	v_add_co_u32_e32 v198, vcc, 0xffffffa0, v198
	s_nop 1
	v_addc_co_u32_e32 v199, vcc, -1, v199, vcc
	flat_store_dword v[198:199], v200
	s_andn2_saveexec_b64 s[24:25], s[92:93]
	s_cbranch_execnz .LBB0_1131

; DI float softplus_fast(float x) { return fmaxf(x, 0.f) + __logf(1.f + __expf(-fabsf(x))); }
.LBB0_1117:
	v_lshl_add_u64 v[198:199], v[152:153], 2, s[28:29]
	v_mov_b32_e32 v198, v234
	v_add_f32_e32 v198, v18, v198
	v_max_f32_e32 v199, 0, v198
	v_mul_f32_e64 v198, |v198|, s46
	v_exp_f32_e32 v198, v198
	s_nop 0
	v_add_f32_e32 v198, 1.0, v198
	v_cmp_gt_f32_e32 vcc, s47, v198
	s_nop 1
	v_cndmask_b32_e64 v200, 0, 32, vcc
	v_ldexp_f32 v198, v198, v200
	v_log_f32_e32 v198, v198
	s_nop 0
	v_mul_f32_e32 v200, 0x3f317217, v198
	v_fma_f32 v200, v198, s94, -v200
	v_fmac_f32_e32 v200, 0x3377d1cf, v198
	v_fmac_f32_e32 v200, 0x3f317217, v198
	v_cmp_lt_f32_e64 s[24:25], |v198|, s51
	s_nop 1
	v_cndmask_b32_e64 v198, v198, v200, s[24:25]
	v_cndmask_b32_e32 v200, 0, v194, vcc
	v_sub_f32_e32 v198, v198, v200
	v_add_f32_e32 v200, v199, v198
	v_lshlrev_b64 v[198:199], 6, v[186:187]
	v_lshl_add_u64 v[198:199], s[42:43], 0, v[198:199]
	v_lshl_add_u64 v[198:199], v[136:137], 2, v[198:199]
	v_add_co_u32_e32 v198, vcc, 0xffffffa0, v198
	s_nop 1
	v_addc_co_u32_e32 v199, vcc, -1, v199, vcc
	flat_store_dword v[198:199], v200
	s_andn2_saveexec_b64 s[24:25], s[92:93]
	s_cbranch_execnz .LBB0_1133

; DI float softplus_fast(float x) { return fmaxf(x, 0.f) + __logf(1.f + __expf(-fabsf(x))); }
.LBB0_1119:
	v_lshl_add_u64 v[198:199], v[152:153], 2, s[28:29]
	v_mov_b32_e32 v198, v235
	v_lshlrev_b64 v[186:187], 6, v[186:187]
	v_lshl_add_u64 v[186:187], s[42:43], 0, v[186:187]
	v_lshl_add_u64 v[186:187], v[132:133], 2, v[186:187]
	v_add_f32_e32 v198, v19, v198
	v_max_f32_e32 v199, 0, v198
	v_mul_f32_e64 v198, |v198|, s46
	v_exp_f32_e32 v198, v198
	s_nop 0
	v_add_f32_e32 v198, 1.0, v198
	v_cmp_gt_f32_e32 vcc, s47, v198
	s_nop 1
	v_cndmask_b32_e64 v200, 0, 32, vcc
	v_ldexp_f32 v198, v198, v200
	v_log_f32_e32 v198, v198
	s_nop 0
	v_mul_f32_e32 v200, 0x3f317217, v198
	v_fma_f32 v200, v198, s94, -v200
	v_fmac_f32_e32 v200, 0x3377d1cf, v198
	v_fmac_f32_e32 v200, 0x3f317217, v198
	v_cmp_lt_f32_e64 s[24:25], |v198|, s51
	s_nop 1
	v_cndmask_b32_e64 v198, v198, v200, s[24:25]
	v_cndmask_b32_e32 v200, 0, v194, vcc
	v_sub_f32_e32 v198, v198, v200
	v_add_co_u32_e32 v186, vcc, 0xffffffa0, v186
	v_add_f32_e32 v198, v199, v198
	s_nop 0
	v_addc_co_u32_e32 v187, vcc, -1, v187, vcc
	flat_store_dword v[186:187], v198
	s_andn2_saveexec_b64 s[24:25], s[92:93]
	s_cbranch_execnz .LBB0_1135
	s_branch .LBB0_1136

; #define TS_(e) { const unsigned w0_ = pk2(ta0[e], ta1[e]); vt[(size_t)(e) * SEQ] = (bf16_t)(w0_ & 0xffff); vt[(size_t)((e) + 4) * SEQ] = (bf16_t)(w0_ >> 16); }
; #define GV_(n, e) { const int c_ = cb + 4 * (n) + (e); const float v_ = (n) ? tb1[e] : tb0[e]; if (c_ < 24) GATES[(size_t)row * 24 + c_] = sigmoidf_(v_); else if (c_ < 40) DT[(size_t)row * 16 + c_ - 24] = softplus_fast(v_ + dt_bias[c_ - 24]); }
;     DI void operator()(const Acc& acc, const Unit& u, int wr, int wc, int fr, int fq) const {
;     ...
;                 else { bf16_t* vt = VWT + ((size_t)(b * 2 + h) * 64 + d0) * SEQ + t; const f32x4 ta0 = acc[ai][0][m][0], ta1 = acc[ai][0][m][1]; TS_(0) TS_(1) TS_(2) TS_(3)
;                   const int cb = wc * 32 + 8 * fq; const f32x4 tb0 = acc[ai][1][m][0], tb1 = acc[ai][1][m][1];
;                   if (cb < 40) { GV_(0, 0) GV_(0, 1) GV_(0, 2) GV_(0, 3) GV_(1, 0) GV_(1, 1) GV_(1, 2) GV_(1, 3) } } )
.LBB0_1139:
	v_add_u32_e32 v182, 0xb0, v182
	v_and_b32_e32 v186, 0x1fff, v182
	v_ashrrev_i32_e32 v187, 13, v182
	s_and_b64 vcc, exec, s[22:23]
	s_mov_b64 s[22:23], -1
	s_cbranch_vccnz .LBB0_1174
	v_lshl_or_b32 v198, v187, 1, s63
	v_ashrrev_i32_e32 v199, 31, v198
	v_lshlrev_b64 v[198:199], 20, v[198:199]
	v_lshl_add_u64 v[180:181], v[180:181], 0, v[198:199]
	v_lshlrev_b32_e32 v198, 1, v186
	v_mov_b32_e32 v199, v153
	v_lshl_add_u64 v[180:181], v[180:181], 0, v[198:199]
	v_add_co_u32_e32 v198, vcc, 0x10000, v180
	v_cvt_pk_bf16_f32 v183, v12, v8
	s_nop 0
	v_addc_co_u32_e32 v199, vcc, 0, v181, vcc
	flat_store_short_d16_hi v[198:199], v183
	v_add_co_u32_e32 v198, vcc, 0x4000, v180
	flat_store_short v[180:181], v183
	v_cvt_pk_bf16_f32 v183, v13, v9
	v_addc_co_u32_e32 v199, vcc, 0, v181, vcc
	flat_store_short v[198:199], v183
	v_add_co_u32_e32 v198, vcc, 0x14000, v180
	s_nop 1
	v_addc_co_u32_e32 v199, vcc, 0, v181, vcc
	flat_store_short_d16_hi v[198:199], v183
	v_add_co_u32_e32 v198, vcc, 0x8000, v180
	v_cvt_pk_bf16_f32 v183, v14, v10
	s_nop 0
	v_addc_co_u32_e32 v199, vcc, 0, v181, vcc
	flat_store_short v[198:199], v183
	v_add_co_u32_e32 v198, vcc, 0x18000, v180
	s_nop 1
	v_addc_co_u32_e32 v199, vcc, 0, v181, vcc
	flat_store_short_d16_hi v[198:199], v183
	v_add_co_u32_e32 v198, vcc, 0xc000, v180
	v_cvt_pk_bf16_f32 v183, v15, v11
	s_nop 0
	v_addc_co_u32_e32 v199, vcc, 0, v181, vcc
	v_add_co_u32_e32 v180, vcc, 0x1c000, v180
	flat_store_short v[198:199], v183
	s_nop 0
	v_addc_co_u32_e32 v181, vcc, 0, v181, vcc
	flat_store_short_d16_hi v[180:181], v183
	s_and_saveexec_b64 s[22:23], s[20:21]
	s_cbranch_execz .LBB0_1173
	v_ashrrev_i32_e32 v183, 31, v182
	v_lshl_add_u64 v[180:181], v[152:153], 2, s[28:29]
	s_and_saveexec_b64 s[20:21], s[18:19]
	s_xor_b64 s[20:21], exec, s[20:21]
	s_cbranch_execz .LBB0_1157
	v_mov_b32_e32 v152, v228
	v_add_f32_e32 v152, v4, v152
	v_max_f32_e32 v178, 0, v152
	v_mul_f32_e64 v152, |v152|, s46
	v_exp_f32_e32 v152, v152
	s_nop 0
	v_add_f32_e32 v152, 1.0, v152
	v_cmp_gt_f32_e32 vcc, s47, v152
	s_nop 1
	v_cndmask_b32_e64 v179, 0, 32, vcc
	v_ldexp_f32 v152, v152, v179
	v_log_f32_e32 v152, v152
	s_nop 0
	v_mul_f32_e32 v179, 0x3f317217, v152
	v_fma_f32 v179, v152, s94, -v179
	v_fmac_f32_e32 v179, 0x3377d1cf, v152
	v_fmac_f32_e32 v179, 0x3f317217, v152
	v_cmp_lt_f32_e64 s[18:19], |v152|, s51
	s_nop 1
	v_cndmask_b32_e64 v152, v152, v179, s[18:19]
	v_cndmask_b32_e32 v179, 0, v194, vcc
	v_sub_f32_e32 v152, v152, v179
	v_add_f32_e32 v152, v178, v152
	v_lshlrev_b64 v[178:179], 6, v[182:183]
	v_lshl_add_u64 v[176:177], v[176:177], 0, v[178:179]
	v_add_co_u32_e32 v176, vcc, 0xffffffa0, v176
	s_nop 1
	v_addc_co_u32_e32 v177, vcc, -1, v177, vcc
	flat_store_dword v[176:177], v152
	s_andn2_saveexec_b64 s[18:19], s[20:21]
	s_cbranch_execnz .LBB0_1158

; DI float softplus_fast(float x) { return fmaxf(x, 0.f) + __logf(1.f + __expf(-fabsf(x))); }
.LBB0_1144:
	v_mov_b32_e32 v152, v229
	v_add_f32_e32 v152, v5, v152
	v_max_f32_e32 v172, 0, v152
	v_mul_f32_e64 v152, |v152|, s46
	v_exp_f32_e32 v152, v152
	s_nop 0
	v_add_f32_e32 v152, 1.0, v152
	v_cmp_gt_f32_e32 vcc, s47, v152
	s_nop 1
	v_cndmask_b32_e64 v173, 0, 32, vcc
	v_ldexp_f32 v152, v152, v173
	v_log_f32_e32 v152, v152
	s_nop 0
	v_mul_f32_e32 v173, 0x3f317217, v152
	v_fma_f32 v173, v152, s94, -v173
	v_fmac_f32_e32 v173, 0x3377d1cf, v152
	v_fmac_f32_e32 v173, 0x3f317217, v152
	v_cmp_lt_f32_e64 s[16:17], |v152|, s51
	s_nop 1
	v_cndmask_b32_e64 v152, v152, v173, s[16:17]
	v_cndmask_b32_e32 v173, 0, v194, vcc
	v_sub_f32_e32 v152, v152, v173
	v_add_f32_e32 v152, v172, v152
	v_lshlrev_b64 v[172:173], 6, v[182:183]
	v_lshl_add_u64 v[172:173], s[42:43], 0, v[172:173]
	v_lshl_add_u64 v[172:173], v[174:175], 2, v[172:173]
	v_add_co_u32_e32 v172, vcc, 0xffffffa0, v172
	s_nop 1
	v_addc_co_u32_e32 v173, vcc, -1, v173, vcc
	flat_store_dword v[172:173], v152
	s_andn2_saveexec_b64 s[16:17], s[18:19]
	s_cbranch_execnz .LBB0_1160

; DI float softplus_fast(float x) { return fmaxf(x, 0.f) + __logf(1.f + __expf(-fabsf(x))); }
.LBB0_1146:
	v_mov_b32_e32 v152, v230
	v_add_f32_e32 v152, v6, v152
	v_max_f32_e32 v168, 0, v152
	v_mul_f32_e64 v152, |v152|, s46
	v_exp_f32_e32 v152, v152
	s_nop 0
	v_add_f32_e32 v152, 1.0, v152
	v_cmp_gt_f32_e32 vcc, s47, v152
	s_nop 1
	v_cndmask_b32_e64 v169, 0, 32, vcc
	v_ldexp_f32 v152, v152, v169
	v_log_f32_e32 v152, v152
	s_nop 0
	v_mul_f32_e32 v169, 0x3f317217, v152
	v_fma_f32 v169, v152, s94, -v169
	v_fmac_f32_e32 v169, 0x3377d1cf, v152
	v_fmac_f32_e32 v169, 0x3f317217, v152
	v_cmp_lt_f32_e64 s[14:15], |v152|, s51
	s_nop 1
	v_cndmask_b32_e64 v152, v152, v169, s[14:15]
	v_cndmask_b32_e32 v169, 0, v194, vcc
	v_sub_f32_e32 v152, v152, v169
	v_add_f32_e32 v152, v168, v152
	v_lshlrev_b64 v[168:169], 6, v[182:183]
	v_lshl_add_u64 v[168:169], s[42:43], 0, v[168:169]
	v_lshl_add_u64 v[168:169], v[170:171], 2, v[168:169]
	v_add_co_u32_e32 v168, vcc, 0xffffffa0, v168
	s_nop 1
	v_addc_co_u32_e32 v169, vcc, -1, v169, vcc
	flat_store_dword v[168:169], v152
	s_andn2_saveexec_b64 s[14:15], s[16:17]
	s_cbranch_execnz .LBB0_1162

; DI float softplus_fast(float x) { return fmaxf(x, 0.f) + __logf(1.f + __expf(-fabsf(x))); }
.LBB0_1148:
	v_mov_b32_e32 v152, v231
	v_add_f32_e32 v152, v7, v152
	v_max_f32_e32 v164, 0, v152
	v_mul_f32_e64 v152, |v152|, s46
	v_exp_f32_e32 v152, v152
	s_nop 0
	v_add_f32_e32 v152, 1.0, v152
	v_cmp_gt_f32_e32 vcc, s47, v152
	s_nop 1
	v_cndmask_b32_e64 v165, 0, 32, vcc
	v_ldexp_f32 v152, v152, v165
	v_log_f32_e32 v152, v152
	s_nop 0
	v_mul_f32_e32 v165, 0x3f317217, v152
	v_fma_f32 v165, v152, s94, -v165
	v_fmac_f32_e32 v165, 0x3377d1cf, v152
	v_fmac_f32_e32 v165, 0x3f317217, v152
	v_cmp_lt_f32_e64 s[12:13], |v152|, s51
	s_nop 1
	v_cndmask_b32_e64 v152, v152, v165, s[12:13]
	v_cndmask_b32_e32 v165, 0, v194, vcc
	v_sub_f32_e32 v152, v152, v165
	v_add_f32_e32 v152, v164, v152
	v_lshlrev_b64 v[164:165], 6, v[182:183]
	v_lshl_add_u64 v[164:165], s[42:43], 0, v[164:165]
	v_lshl_add_u64 v[164:165], v[166:167], 2, v[164:165]
	v_add_co_u32_e32 v164, vcc, 0xffffffa0, v164
	s_nop 1
	v_addc_co_u32_e32 v165, vcc, -1, v165, vcc
	flat_store_dword v[164:165], v152
	s_andn2_saveexec_b64 s[12:13], s[14:15]
	s_cbranch_execnz .LBB0_1164

; DI float softplus_fast(float x) { return fmaxf(x, 0.f) + __logf(1.f + __expf(-fabsf(x))); }
.LBB0_1150:
	v_mov_b32_e32 v142, v232
	v_add_f32_e32 v142, v0, v142
	v_max_f32_e32 v143, 0, v142
	v_mul_f32_e64 v142, |v142|, s46
	v_exp_f32_e32 v142, v142
	s_nop 0
	v_add_f32_e32 v142, 1.0, v142
	v_cmp_gt_f32_e32 vcc, s47, v142
	s_nop 1
	v_cndmask_b32_e64 v152, 0, 32, vcc
	v_ldexp_f32 v142, v142, v152
	v_log_f32_e32 v142, v142
	s_nop 0
	v_mul_f32_e32 v152, 0x3f317217, v142
	v_fma_f32 v152, v142, s94, -v152
	v_fmac_f32_e32 v152, 0x3377d1cf, v142
	v_fmac_f32_e32 v152, 0x3f317217, v142
	v_cmp_lt_f32_e64 s[10:11], |v142|, s51
	s_nop 1
	v_cndmask_b32_e64 v142, v142, v152, s[10:11]
	v_cndmask_b32_e32 v152, 0, v194, vcc
	v_sub_f32_e32 v142, v142, v152
	v_add_f32_e32 v152, v143, v142
	v_lshlrev_b64 v[142:143], 6, v[182:183]
	v_lshl_add_u64 v[142:143], s[42:43], 0, v[142:143]
	v_lshl_add_u64 v[142:143], v[162:163], 2, v[142:143]
	v_add_co_u32_e32 v142, vcc, 0xffffffa0, v142
	s_nop 1
	v_addc_co_u32_e32 v143, vcc, -1, v143, vcc
	flat_store_dword v[142:143], v152
	s_andn2_saveexec_b64 s[10:11], s[12:13]
	s_cbranch_execnz .LBB0_1166

; DI float softplus_fast(float x) { return fmaxf(x, 0.f) + __logf(1.f + __expf(-fabsf(x))); }
.LBB0_1152:
	v_mov_b32_e32 v138, v233
	v_add_f32_e32 v138, v1, v138
	v_max_f32_e32 v139, 0, v138
	v_mul_f32_e64 v138, |v138|, s46
	v_exp_f32_e32 v138, v138
	s_nop 0
	v_add_f32_e32 v138, 1.0, v138
	v_cmp_gt_f32_e32 vcc, s47, v138
	s_nop 1
	v_cndmask_b32_e64 v142, 0, 32, vcc
	v_ldexp_f32 v138, v138, v142
	v_log_f32_e32 v138, v138
	s_nop 0
	v_mul_f32_e32 v142, 0x3f317217, v138
	v_fma_f32 v142, v138, s94, -v142
	v_fmac_f32_e32 v142, 0x3377d1cf, v138
	v_fmac_f32_e32 v142, 0x3f317217, v138
	v_cmp_lt_f32_e64 s[8:9], |v138|, s51
	s_nop 1
	v_cndmask_b32_e64 v138, v138, v142, s[8:9]
	v_cndmask_b32_e32 v142, 0, v194, vcc
	v_sub_f32_e32 v138, v138, v142
	v_add_f32_e32 v142, v139, v138
	v_lshlrev_b64 v[138:139], 6, v[182:183]
	v_lshl_add_u64 v[138:139], s[42:43], 0, v[138:139]
	v_lshl_add_u64 v[138:139], v[140:141], 2, v[138:139]
	v_add_co_u32_e32 v138, vcc, 0xffffffa0, v138
	s_nop 1
	v_addc_co_u32_e32 v139, vcc, -1, v139, vcc
	flat_store_dword v[138:139], v142
	s_andn2_saveexec_b64 s[8:9], s[10:11]
	s_cbranch_execnz .LBB0_1168

; DI float softplus_fast(float x) { return fmaxf(x, 0.f) + __logf(1.f + __expf(-fabsf(x))); }
.LBB0_1154:
	v_mov_b32_e32 v134, v234
	v_add_f32_e32 v134, v2, v134
	v_max_f32_e32 v135, 0, v134
	v_mul_f32_e64 v134, |v134|, s46
	v_exp_f32_e32 v134, v134
	s_nop 0
	v_add_f32_e32 v134, 1.0, v134
	v_cmp_gt_f32_e32 vcc, s47, v134
	s_nop 1
	v_cndmask_b32_e64 v138, 0, 32, vcc
	v_ldexp_f32 v134, v134, v138
	v_log_f32_e32 v134, v134
	s_nop 0
	v_mul_f32_e32 v138, 0x3f317217, v134
	v_fma_f32 v138, v134, s94, -v138
	v_fmac_f32_e32 v138, 0x3377d1cf, v134
	v_fmac_f32_e32 v138, 0x3f317217, v134
	v_cmp_lt_f32_e64 s[6:7], |v134|, s51
	s_nop 1
	v_cndmask_b32_e64 v134, v134, v138, s[6:7]
	v_cndmask_b32_e32 v138, 0, v194, vcc
	v_sub_f32_e32 v134, v134, v138
	v_add_f32_e32 v138, v135, v134
	v_lshlrev_b64 v[134:135], 6, v[182:183]
	v_lshl_add_u64 v[134:135], s[42:43], 0, v[134:135]
	v_lshl_add_u64 v[134:135], v[136:137], 2, v[134:135]
	v_add_co_u32_e32 v134, vcc, 0xffffffa0, v134
	s_nop 1
	v_addc_co_u32_e32 v135, vcc, -1, v135, vcc
	flat_store_dword v[134:135], v138
	s_andn2_saveexec_b64 s[6:7], s[8:9]
	s_cbranch_execnz .LBB0_1170

; DI float softplus_fast(float x) { return fmaxf(x, 0.f) + __logf(1.f + __expf(-fabsf(x))); }
.LBB0_1156:
	v_mov_b32_e32 v130, v235
	v_add_f32_e32 v134, v3, v130
	v_mul_f32_e64 v130, |v134|, s46
	v_exp_f32_e32 v135, v130
	v_lshlrev_b64 v[130:131], 6, v[182:183]
	v_lshl_add_u64 v[130:131], s[42:43], 0, v[130:131]
	v_lshl_add_u64 v[130:131], v[132:133], 2, v[130:131]
	v_add_f32_e32 v132, 1.0, v135
	v_cmp_gt_f32_e64 s[4:5], s47, v132
	v_add_co_u32_e32 v130, vcc, 0xffffffa0, v130
	s_nop 0
	v_cndmask_b32_e64 v133, 0, 32, s[4:5]
	v_ldexp_f32 v132, v132, v133
	v_log_f32_e32 v132, v132
	v_max_f32_e32 v133, 0, v134
	v_cndmask_b32_e64 v134, 0, v194, s[4:5]
	v_addc_co_u32_e32 v131, vcc, -1, v131, vcc
	v_mul_f32_e32 v135, 0x3f317217, v132
	v_fma_f32 v135, v132, s94, -v135
	v_fmac_f32_e32 v135, 0x3377d1cf, v132
	v_fmac_f32_e32 v135, 0x3f317217, v132
	v_cmp_lt_f32_e64 s[4:5], |v132|, s51
	s_nop 1
	v_cndmask_b32_e64 v132, v132, v135, s[4:5]
	v_sub_f32_e32 v132, v132, v134
	v_add_f32_e32 v132, v133, v132
	flat_store_dword v[130:131], v132
	s_andn2_saveexec_b64 s[4:5], s[6:7]
	s_cbranch_execnz .LBB0_1172
	s_branch .LBB0_1173
